# baseline (speedup 1.0000x reference)
; #define PG8_STAGE(bufoff, gbase, voff) do { _Pragma("unroll") for (int _i = 0; _i < 2; ++_i) \
;         __builtin_amdgcn_global_load_lds((const unsigned*)((const char*)(gbase) + (voff)[_i]), (PG8_LAS unsigned*)(lds + (bufoff) + ldsw + _i * 8192), 16, 0, 0); } while (0)
; #define PG8_WAIT_V(n) asm volatile("s_waitcnt vmcnt(" #n ")" ::: "memory")
; #define PG8_WAIT_L(n) asm volatile("s_waitcnt lgkmcnt(" #n ")" ::: "memory")
; #define PG8_BAR __builtin_amdgcn_s_barrier()
; #define PG8_SCHED __builtin_amdgcn_sched_barrier(0)
; template <class Epi, class Sched, bool ALIGN_EPI = false, bool SP2 = false, bool FP8 = false>
; __device__ __forceinline__ void gemm_phase(PG8_LAS unsigned char* lds, const Gemm g, const Sched& S, const Epi& E, const int tid) {
;     ...
;             PG8_WAIT_V(8); PG8_WAIT_L(0); PG8_BAR; PG8_MMA(1, 0, At, B0); PG8_MMA(1, 1, At, B1); PG8_BAR; PG8_SCHED;
;             PG8_LDB(B0, 1, 0); PG8_LDB(B1, 1, 1); PG8_SCHED; PG8_LDA(At, 1, 0); PG8_STAGE(PG8_SA(0, 1), a2 + hstepA, voffA);
;             PG8_WAIT_V(8); PG8_WAIT_L(0); PG8_BAR; PG8_MMA(0, 0, At, B0); PG8_MMA(0, 1, At, B1); PG8_BAR; PG8_SCHED;
.Lskw_0_1:
	s_waitcnt lgkmcnt(0)
	s_barrier
	s_setprio 1
	s_waitcnt lgkmcnt(0)
	s_nop 0
	v_mfma_f32_16x16x32_bf16 v[62:65], v[142:145], v[196:199], v[62:65]
	v_mfma_f32_16x16x32_bf16 v[58:61], v[154:157], v[196:199], v[58:61]
	v_mfma_f32_16x16x32_bf16 v[46:49], v[142:145], v[224:227], v[46:49]
	v_mfma_f32_16x16x32_bf16 v[42:45], v[154:157], v[224:227], v[42:45]
	v_mfma_f32_16x16x32_bf16 v[28:31], v[142:145], v[232:235], v[28:31]
	v_mfma_f32_16x16x32_bf16 v[24:27], v[154:157], v[232:235], v[24:27]
	v_mfma_f32_16x16x32_bf16 v[12:15], v[142:145], v[240:243], v[12:15]
	v_mfma_f32_16x16x32_bf16 v[8:11], v[154:157], v[240:243], v[8:11]
	v_mfma_f32_16x16x32_bf16 v[62:65], v[146:149], v[220:223], v[62:65]
	v_mfma_f32_16x16x32_bf16 v[58:61], v[158:161], v[220:223], v[58:61]
	v_mfma_f32_16x16x32_bf16 v[46:49], v[146:149], v[228:231], v[46:49]
	v_mfma_f32_16x16x32_bf16 v[42:45], v[158:161], v[228:231], v[42:45]
	v_mfma_f32_16x16x32_bf16 v[28:31], v[146:149], v[236:239], v[28:31]
	v_mfma_f32_16x16x32_bf16 v[24:27], v[158:161], v[236:239], v[24:27]
	v_mfma_f32_16x16x32_bf16 v[12:15], v[146:149], v[244:247], v[12:15]
	v_mfma_f32_16x16x32_bf16 v[8:11], v[158:161], v[244:247], v[8:11]
	s_setprio 0
	s_setprio 1
	v_mfma_f32_16x16x32_bf16 v[54:57], v[180:183], v[196:199], v[54:57]
	v_mfma_f32_16x16x32_bf16 v[50:53], v[188:191], v[196:199], v[50:53]
	v_mfma_f32_16x16x32_bf16 v[38:41], v[180:183], v[224:227], v[38:41]
	v_mfma_f32_16x16x32_bf16 v[34:37], v[188:191], v[224:227], v[34:37]
	v_mfma_f32_16x16x32_bf16 v[20:23], v[180:183], v[232:235], v[20:23]
	v_mfma_f32_16x16x32_bf16 v[16:19], v[188:191], v[232:235], v[16:19]
	v_mfma_f32_16x16x32_bf16 v[4:7], v[180:183], v[240:243], v[4:7]
	v_mfma_f32_16x16x32_bf16 v[0:3], v[188:191], v[240:243], v[0:3]
	v_mfma_f32_16x16x32_bf16 v[54:57], v[184:187], v[220:223], v[54:57]
	v_mfma_f32_16x16x32_bf16 v[50:53], v[192:195], v[220:223], v[50:53]
	v_mfma_f32_16x16x32_bf16 v[38:41], v[184:187], v[228:231], v[38:41]
	v_mfma_f32_16x16x32_bf16 v[34:37], v[192:195], v[228:231], v[34:37]
	v_mfma_f32_16x16x32_bf16 v[20:23], v[184:187], v[236:239], v[20:23]
	v_mfma_f32_16x16x32_bf16 v[16:19], v[192:195], v[236:239], v[16:19]
	v_mfma_f32_16x16x32_bf16 v[4:7], v[184:187], v[244:247], v[4:7]
	v_mfma_f32_16x16x32_bf16 v[0:3], v[192:195], v[244:247], v[0:3]
	s_setprio 0
	s_barrier
	s_add_i32 s57, 0, 0x18000
	v_add_u32_e32 v153, s57, v150
	s_add_i32 s58, 0, 0x1c000
	ds_read_b128 v[142:145], v153
	ds_read_b128 v[146:149], v153 offset:1024
	ds_read_b128 v[154:157], v153 offset:2048
	ds_read_b128 v[158:161], v153 offset:3072
	v_add_u32_e32 v153, s58, v150
	ds_read_b128 v[180:183], v153
	ds_read_b128 v[184:187], v153 offset:1024
	ds_read_b128 v[188:191], v153 offset:2048
	ds_read_b128 v[192:195], v153 offset:3072
	s_add_u32 s40, s40, 0x80000
	s_addc_u32 s41, s41, 0
	s_mov_b32 m0, s45
	v_lshl_add_u64 v[166:167], s[40:41], 0, v[136:137]
	ds_read_b128 v[196:199], v152 offset:32768
	ds_read_b128 v[220:223], v152 offset:33792
	ds_read_b128 v[224:227], v152 offset:34816
	ds_read_b128 v[228:231], v152 offset:35840
	ds_read_b128 v[232:235], v152 offset:36864
	ds_read_b128 v[236:239], v152 offset:37888
	ds_read_b128 v[240:243], v152 offset:38912
	ds_read_b128 v[244:247], v152 offset:39936
	global_load_lds_dwordx4 v[166:167], off
	v_lshl_add_u64 v[166:167], s[40:41], 0, v[132:133]
	s_mov_b32 m0, s46
	s_nop 0
	global_load_lds_dwordx4 v[166:167], off
	s_waitcnt vmcnt(8)
	s_waitcnt lgkmcnt(0)
	s_barrier
	s_setprio 1
	s_waitcnt lgkmcnt(0)
	s_nop 0
	v_mfma_f32_16x16x32_bf16 v[126:129], v[142:145], v[196:199], v[126:129]
	v_mfma_f32_16x16x32_bf16 v[122:125], v[154:157], v[196:199], v[122:125]
	v_mfma_f32_16x16x32_bf16 v[110:113], v[142:145], v[224:227], v[110:113]
	v_mfma_f32_16x16x32_bf16 v[106:109], v[154:157], v[224:227], v[106:109]
	v_mfma_f32_16x16x32_bf16 v[94:97], v[142:145], v[232:235], v[94:97]
	v_mfma_f32_16x16x32_bf16 v[90:93], v[154:157], v[232:235], v[90:93]
	v_mfma_f32_16x16x32_bf16 v[78:81], v[142:145], v[240:243], v[78:81]
	v_mfma_f32_16x16x32_bf16 v[74:77], v[154:157], v[240:243], v[74:77]
	v_mfma_f32_16x16x32_bf16 v[126:129], v[146:149], v[220:223], v[126:129]
	v_mfma_f32_16x16x32_bf16 v[122:125], v[158:161], v[220:223], v[122:125]
	v_mfma_f32_16x16x32_bf16 v[110:113], v[146:149], v[228:231], v[110:113]
	v_mfma_f32_16x16x32_bf16 v[106:109], v[158:161], v[228:231], v[106:109]
	v_mfma_f32_16x16x32_bf16 v[94:97], v[146:149], v[236:239], v[94:97]
	v_mfma_f32_16x16x32_bf16 v[90:93], v[158:161], v[236:239], v[90:93]
	v_mfma_f32_16x16x32_bf16 v[78:81], v[146:149], v[244:247], v[78:81]
	v_mfma_f32_16x16x32_bf16 v[74:77], v[158:161], v[244:247], v[74:77]
	s_setprio 0
	s_setprio 1
	v_mfma_f32_16x16x32_bf16 v[118:121], v[180:183], v[196:199], v[118:121]
	v_mfma_f32_16x16x32_bf16 v[114:117], v[188:191], v[196:199], v[114:117]
	v_mfma_f32_16x16x32_bf16 v[102:105], v[180:183], v[224:227], v[102:105]
	v_mfma_f32_16x16x32_bf16 v[98:101], v[188:191], v[224:227], v[98:101]
	v_mfma_f32_16x16x32_bf16 v[86:89], v[180:183], v[232:235], v[86:89]
	v_mfma_f32_16x16x32_bf16 v[82:85], v[188:191], v[232:235], v[82:85]
	v_mfma_f32_16x16x32_bf16 v[70:73], v[180:183], v[240:243], v[70:73]
	v_mfma_f32_16x16x32_bf16 v[66:69], v[188:191], v[240:243], v[66:69]
	v_mfma_f32_16x16x32_bf16 v[118:121], v[184:187], v[220:223], v[118:121]
	v_mfma_f32_16x16x32_bf16 v[114:117], v[192:195], v[220:223], v[114:117]
	v_mfma_f32_16x16x32_bf16 v[102:105], v[184:187], v[228:231], v[102:105]
	v_mfma_f32_16x16x32_bf16 v[98:101], v[192:195], v[228:231], v[98:101]
	v_mfma_f32_16x16x32_bf16 v[86:89], v[184:187], v[236:239], v[86:89]
	v_mfma_f32_16x16x32_bf16 v[82:85], v[192:195], v[236:239], v[82:85]
	v_mfma_f32_16x16x32_bf16 v[70:73], v[184:187], v[244:247], v[70:73]
	v_mfma_f32_16x16x32_bf16 v[66:69], v[192:195], v[244:247], v[66:69]
	s_setprio 0
	s_barrier
; #define PG8_STAGE(bufoff, gbase, voff) do { _Pragma("unroll") for (int _i = 0; _i < 2; ++_i) \
;         __builtin_amdgcn_global_load_lds((const unsigned*)((const char*)(gbase) + (voff)[_i]), (PG8_LAS unsigned*)(lds + (bufoff) + ldsw + _i * 8192), 16, 0, 0); } while (0)
; #define PG8_WAIT_V(n) asm volatile("s_waitcnt vmcnt(" #n ")" ::: "memory")
; #define PG8_WAIT_L(n) asm volatile("s_waitcnt lgkmcnt(" #n ")" ::: "memory")
; #define PG8_BAR __builtin_amdgcn_s_barrier()
; #define PG8_SCHED __builtin_amdgcn_sched_barrier(0)
;     __device__ __forceinline__ void operator()(const f32x4 (&acc)[2][2][4][2], const Unit& u, int wr, int wc, int fr, int fq) const {
;     ...
;             for (int m = 0; m < 4; ++m) { const int row = row0 + ai * HALF + m * 16; const float rs = __builtin_amdgcn_rsqf((float)ss[row] * (SS_INV / 2048.0f) + RMS_EPS) * osc;
; template <class Epi, class Sched, bool ALIGN_EPI = false, bool SP2 = false, bool FP8 = false>
; __device__ __forceinline__ void gemm_phase(PG8_LAS unsigned char* lds, const Gemm g, const Sched& S, const Epi& E, const int tid) {
;     ...
;             PG8_LDA(At, 1, 1); PG8_STAGE(PG8_SB(1, 0), b3, voffB); PG8_STAGE(PG8_SB(1, 1), b3 + hstepB, voffB); PG8_STAGE(PG8_SA(1, 0), a3, voffA);
;             PG8_WAIT_V(8); PG8_WAIT_L(0); PG8_BAR; PG8_MMA(1, 0, At, B0); PG8_MMA(1, 1, At, B1); PG8_BAR; PG8_SCHED;
	s_add_i32 s40, s57, s42
	v_lshl_add_u64 v[166:167], v[200:201], 0, s[38:39]
	s_mov_b32 m0, s40
	ds_read_b128 v[196:199], v152 offset:49152
	ds_read_b128 v[220:223], v152 offset:50176
	ds_read_b128 v[224:227], v152 offset:51200
	ds_read_b128 v[228:231], v152 offset:52224
	ds_read_b128 v[232:235], v152 offset:53248
	ds_read_b128 v[236:239], v152 offset:54272
	ds_read_b128 v[240:243], v152 offset:55296
	ds_read_b128 v[244:247], v152 offset:56320
	global_load_lds_dwordx4 v[166:167], off
	s_add_i32 m0, s40, 0x2000
	s_add_u32 s36, s36, 0x80080
	v_lshl_add_u64 v[166:167], v[248:249], 0, s[38:39]
	s_addc_u32 s37, s37, 0
	s_add_i32 s40, s58, s42
	global_load_lds_dwordx4 v[166:167], off
	v_lshl_add_u64 v[166:167], s[36:37], 0, v[134:135]
	s_mov_b32 m0, s40
	v_lshl_add_u64 v[164:165], v[164:165], 0, s[38:39]
	global_load_lds_dwordx4 v[166:167], off
	v_lshl_add_u64 v[166:167], s[36:37], 0, v[130:131]
	s_add_i32 m0, s40, 0x2000
	s_nop 0
	global_load_lds_dwordx4 v[166:167], off
	v_lshl_add_u64 v[166:167], v[250:251], 0, s[38:39]
	s_mov_b32 m0, s47
	s_nop 0
	global_load_lds_dwordx4 v[166:167], off
	s_mov_b32 m0, s48
	s_nop 0
	global_load_lds_dwordx4 v[164:165], off
	s_waitcnt vmcnt(8)
	s_waitcnt lgkmcnt(0)
	s_barrier
	s_setprio 1
	s_waitcnt lgkmcnt(0)
	s_nop 0
	v_mfma_f32_16x16x32_bf16 v[62:65], v[142:145], v[196:199], v[62:65]
	v_mfma_f32_16x16x32_bf16 v[58:61], v[154:157], v[196:199], v[58:61]
	v_mfma_f32_16x16x32_bf16 v[46:49], v[142:145], v[224:227], v[46:49]
	v_mfma_f32_16x16x32_bf16 v[42:45], v[154:157], v[224:227], v[42:45]
	v_mfma_f32_16x16x32_bf16 v[28:31], v[142:145], v[232:235], v[28:31]
	v_mfma_f32_16x16x32_bf16 v[24:27], v[154:157], v[232:235], v[24:27]
	v_mfma_f32_16x16x32_bf16 v[12:15], v[142:145], v[240:243], v[12:15]
	v_mfma_f32_16x16x32_bf16 v[8:11], v[154:157], v[240:243], v[8:11]
	v_mfma_f32_16x16x32_bf16 v[62:65], v[146:149], v[220:223], v[62:65]
	v_mfma_f32_16x16x32_bf16 v[58:61], v[158:161], v[220:223], v[58:61]
	v_mfma_f32_16x16x32_bf16 v[46:49], v[146:149], v[228:231], v[46:49]
	v_mfma_f32_16x16x32_bf16 v[42:45], v[158:161], v[228:231], v[42:45]
	v_mfma_f32_16x16x32_bf16 v[28:31], v[146:149], v[236:239], v[28:31]
	v_mfma_f32_16x16x32_bf16 v[24:27], v[158:161], v[236:239], v[24:27]
	v_mfma_f32_16x16x32_bf16 v[12:15], v[146:149], v[244:247], v[12:15]
	v_mfma_f32_16x16x32_bf16 v[8:11], v[158:161], v[244:247], v[8:11]
	s_setprio 0
	s_setprio 1
	v_mfma_f32_16x16x32_bf16 v[54:57], v[180:183], v[196:199], v[54:57]
	v_mfma_f32_16x16x32_bf16 v[50:53], v[188:191], v[196:199], v[50:53]
	v_mfma_f32_16x16x32_bf16 v[38:41], v[180:183], v[224:227], v[38:41]
	v_mfma_f32_16x16x32_bf16 v[34:37], v[188:191], v[224:227], v[34:37]
	v_mfma_f32_16x16x32_bf16 v[20:23], v[180:183], v[232:235], v[20:23]
	v_mfma_f32_16x16x32_bf16 v[16:19], v[188:191], v[232:235], v[16:19]
	v_mfma_f32_16x16x32_bf16 v[4:7], v[180:183], v[240:243], v[4:7]
	v_mfma_f32_16x16x32_bf16 v[0:3], v[188:191], v[240:243], v[0:3]
	v_mfma_f32_16x16x32_bf16 v[54:57], v[184:187], v[220:223], v[54:57]
	v_mfma_f32_16x16x32_bf16 v[50:53], v[192:195], v[220:223], v[50:53]
	v_mfma_f32_16x16x32_bf16 v[38:41], v[184:187], v[228:231], v[38:41]
	v_mfma_f32_16x16x32_bf16 v[34:37], v[192:195], v[228:231], v[34:37]
	v_mfma_f32_16x16x32_bf16 v[20:23], v[184:187], v[236:239], v[20:23]
	v_mfma_f32_16x16x32_bf16 v[16:19], v[192:195], v[236:239], v[16:19]
	v_mfma_f32_16x16x32_bf16 v[4:7], v[184:187], v[244:247], v[4:7]
	v_mfma_f32_16x16x32_bf16 v[0:3], v[192:195], v[244:247], v[0:3]
	s_setprio 0
	s_barrier
	s_add_i32 s56, s56, 2
	s_add_u32 s34, s34, 0x100
	s_addc_u32 s35, s35, 0
	s_add_u32 s54, s54, 0x100
	s_addc_u32 s55, s55, 0
	s_cmp_gt_u32 s56, 29
	s_cbranch_scc0 .LBB0_98
	v_lshl_add_u32 v142, s51, 8, v33
	v_ashrrev_i32_e32 v143, 31, v142
	v_lshl_add_u64 v[148:149], v[142:143], 3, s[8:9]
	global_load_dwordx2 v[220:221], v[148:149], off
	global_load_dwordx2 v[222:223], v[148:149], off offset:128
	global_load_dwordx2 v[224:225], v[148:149], off offset:256
	global_load_dwordx2 v[226:227], v[148:149], off offset:384
	global_load_dwordx2 v[228:229], v[148:149], off offset:1024
	global_load_dwordx2 v[230:231], v[148:149], off offset:1152
	global_load_dwordx2 v[232:233], v[148:149], off offset:1280
	global_load_dwordx2 v[234:235], v[148:149], off offset:1408
	s_and_b64 vcc, exec, s[16:17]
	s_cbranch_vccz .LBB0_101
	s_barrier

; #define PG8_STAGE(bufoff, gbase, voff) do { _Pragma("unroll") for (int _i = 0; _i < 2; ++_i) \
;         __builtin_amdgcn_global_load_lds((const unsigned*)((const char*)(gbase) + (voff)[_i]), (PG8_LAS unsigned*)(lds + (bufoff) + ldsw + _i * 8192), 16, 0, 0); } while (0)
; #define PG8_WAIT_V(n) asm volatile("s_waitcnt vmcnt(" #n ")" ::: "memory")
; #define PG8_WAIT_L(n) asm volatile("s_waitcnt lgkmcnt(" #n ")" ::: "memory")
; #define PG8_BAR __builtin_amdgcn_s_barrier()
; #define PG8_SCHED __builtin_amdgcn_sched_barrier(0)
;     __device__ __forceinline__ void operator()(const f32x4 (&acc)[2][2][4][2], const Unit& u, int wr, int wc, int fr, int fq) const {
;     ...
;             for (int m = 0; m < 4; ++m) { const int row = row0 + ai * HALF + m * 16; const float rs = __builtin_amdgcn_rsqf((float)ss[row] * (SS_INV / 2048.0f) + RMS_EPS) * osc;
; template <class Epi, class Sched, bool ALIGN_EPI = false, bool SP2 = false, bool FP8 = false>
; __device__ __forceinline__ void gemm_phase(PG8_LAS unsigned char* lds, const Gemm g, const Sched& S, const Epi& E, const int tid) {
;     ...
;             PG8_WAIT_V(8); PG8_WAIT_L(0); PG8_BAR; PG8_MMA(1, 0, At, B0); PG8_MMA(1, 1, At, B1); PG8_BAR; PG8_SCHED;
;             PG8_LDB(B0, 1, 0); PG8_LDB(B1, 1, 1); PG8_SCHED; PG8_LDA(At, 1, 0); PG8_STAGE(PG8_SA(0, 1), a2 + hstepA, voffA);
;             PG8_WAIT_V(8); PG8_WAIT_L(0); PG8_BAR; PG8_MMA(0, 0, At, B0); PG8_MMA(0, 1, At, B1); PG8_BAR; PG8_SCHED;
;             PG8_LDA(At, 1, 1); PG8_STAGE(PG8_SB(1, 0), b3, voffB); PG8_STAGE(PG8_SB(1, 1), b3 + hstepB, voffB); PG8_STAGE(PG8_SA(1, 0), a3, voffA);
;             PG8_WAIT_V(8); PG8_WAIT_L(0); PG8_BAR; PG8_MMA(1, 0, At, B0); PG8_MMA(1, 1, At, B1); PG8_BAR; PG8_SCHED;
.Lskw_1_1:
	s_waitcnt lgkmcnt(0)
	s_barrier
	s_setprio 1
	s_waitcnt lgkmcnt(0)
	v_mfma_f32_16x16x128_f8f6f4 v[94:97], v[16:23], v[220:227], v[94:97]
	v_mfma_f32_16x16x128_f8f6f4 v[90:93], v[24:31], v[220:227], v[90:93]
	v_mfma_f32_16x16x128_f8f6f4 v[78:81], v[16:23], v[228:235], v[78:81]
	v_mfma_f32_16x16x128_f8f6f4 v[74:77], v[24:31], v[228:235], v[74:77]
	v_mfma_f32_16x16x128_f8f6f4 v[62:65], v[16:23], v[236:243], v[62:65]
	v_mfma_f32_16x16x128_f8f6f4 v[58:61], v[24:31], v[236:243], v[58:61]
	v_mfma_f32_16x16x128_f8f6f4 v[46:49], v[16:23], v[244:251], v[46:49]
	v_mfma_f32_16x16x128_f8f6f4 v[42:45], v[24:31], v[244:251], v[42:45]
	s_setprio 0
	s_setprio 1
	v_mfma_f32_16x16x128_f8f6f4 v[86:89], v[0:7], v[220:227], v[86:89]
	v_mfma_f32_16x16x128_f8f6f4 v[82:85], v[8:15], v[220:227], v[82:85]
	v_mfma_f32_16x16x128_f8f6f4 v[70:73], v[0:7], v[228:235], v[70:73]
	v_mfma_f32_16x16x128_f8f6f4 v[66:69], v[8:15], v[228:235], v[66:69]
	v_mfma_f32_16x16x128_f8f6f4 v[54:57], v[0:7], v[236:243], v[54:57]
	v_mfma_f32_16x16x128_f8f6f4 v[50:53], v[8:15], v[236:243], v[50:53]
	v_mfma_f32_16x16x128_f8f6f4 v[38:41], v[0:7], v[244:251], v[38:41]
	v_mfma_f32_16x16x128_f8f6f4 v[34:37], v[8:15], v[244:251], v[34:37]
	s_setprio 0
	s_barrier
	s_add_i32 s55, 0, 0x18000
	s_add_i32 s56, 0, 0x1c000
	v_add_u32_e32 v12, s55, v163
	v_add_u32_e32 v28, s56, v163
	ds_read_b128 v[0:3], v12
	ds_read_b128 v[4:7], v12 offset:1024
	ds_read_b128 v[8:11], v12 offset:2048
	ds_read_b128 v[12:15], v12 offset:3072
	ds_read_b128 v[16:19], v28
	ds_read_b128 v[20:23], v28 offset:1024
	ds_read_b128 v[24:27], v28 offset:2048
	ds_read_b128 v[28:31], v28 offset:3072
	s_add_u32 s36, s36, 0x40000
	s_addc_u32 s37, s37, 0
	s_mov_b32 m0, s47
	v_lshl_add_u64 v[164:165], s[36:37], 0, v[186:187]
	ds_read_b128 v[220:223], v200 offset:32768
	ds_read_b128 v[224:227], v200 offset:33792
	ds_read_b128 v[228:231], v200 offset:34816
	ds_read_b128 v[232:235], v200 offset:35840
	ds_read_b128 v[236:239], v200 offset:36864
	ds_read_b128 v[240:243], v200 offset:37888
	ds_read_b128 v[244:247], v200 offset:38912
	ds_read_b128 v[248:251], v200 offset:39936
	global_load_lds_dwordx4 v[164:165], off
	v_lshl_add_u64 v[164:165], s[36:37], 0, v[182:183]
	s_mov_b32 m0, s48
	s_nop 0
	global_load_lds_dwordx4 v[164:165], off
	s_waitcnt vmcnt(8)
	s_waitcnt lgkmcnt(0)
	s_barrier
	s_setprio 1
	s_waitcnt lgkmcnt(0)
	s_nop 0
	v_mfma_f32_16x16x128_f8f6f4 v[158:161], v[0:7], v[220:227], v[158:161]
	v_mfma_f32_16x16x128_f8f6f4 v[154:157], v[8:15], v[220:227], v[154:157]
	v_mfma_f32_16x16x128_f8f6f4 v[142:145], v[0:7], v[228:235], v[142:145]
	v_mfma_f32_16x16x128_f8f6f4 v[138:141], v[8:15], v[228:235], v[138:141]
	v_mfma_f32_16x16x128_f8f6f4 v[126:129], v[0:7], v[236:243], v[126:129]
	v_mfma_f32_16x16x128_f8f6f4 v[122:125], v[8:15], v[236:243], v[122:125]
	v_mfma_f32_16x16x128_f8f6f4 v[110:113], v[0:7], v[244:251], v[110:113]
	v_mfma_f32_16x16x128_f8f6f4 v[106:109], v[8:15], v[244:251], v[106:109]
	s_setprio 0
	s_setprio 1
	v_mfma_f32_16x16x128_f8f6f4 v[150:153], v[16:23], v[220:227], v[150:153]
	v_mfma_f32_16x16x128_f8f6f4 v[146:149], v[24:31], v[220:227], v[146:149]
	v_mfma_f32_16x16x128_f8f6f4 v[134:137], v[16:23], v[228:235], v[134:137]
	v_mfma_f32_16x16x128_f8f6f4 v[130:133], v[24:31], v[228:235], v[130:133]
	v_mfma_f32_16x16x128_f8f6f4 v[118:121], v[16:23], v[236:243], v[118:121]
	v_mfma_f32_16x16x128_f8f6f4 v[114:117], v[24:31], v[236:243], v[114:117]
	v_mfma_f32_16x16x128_f8f6f4 v[102:105], v[16:23], v[244:251], v[102:105]
	v_mfma_f32_16x16x128_f8f6f4 v[98:101], v[24:31], v[244:251], v[98:101]
	s_setprio 0
	s_barrier
	s_add_i32 s36, s55, s44
	v_lshl_add_u64 v[164:165], v[192:193], 0, s[38:39]
	s_mov_b32 m0, s36
	ds_read_b128 v[220:223], v200 offset:49152
	ds_read_b128 v[224:227], v200 offset:50176
	ds_read_b128 v[228:231], v200 offset:51200
	ds_read_b128 v[232:235], v200 offset:52224
	ds_read_b128 v[236:239], v200 offset:53248
	ds_read_b128 v[240:243], v200 offset:54272
	ds_read_b128 v[244:247], v200 offset:55296
	ds_read_b128 v[248:251], v200 offset:56320
	global_load_lds_dwordx4 v[164:165], off
	s_add_i32 m0, s36, 0x2000
	s_add_u32 s34, s34, 0x40080
	v_lshl_add_u64 v[164:165], v[194:195], 0, s[38:39]
	s_addc_u32 s35, s35, 0
	s_add_i32 s36, s56, s44
	global_load_lds_dwordx4 v[164:165], off
	v_lshl_add_u64 v[164:165], s[34:35], 0, v[184:185]
	s_mov_b32 m0, s36
	s_nop 0
	global_load_lds_dwordx4 v[164:165], off
	v_lshl_add_u64 v[164:165], s[34:35], 0, v[180:181]
	s_add_i32 m0, s36, 0x2000
	s_nop 0
	global_load_lds_dwordx4 v[164:165], off
	v_lshl_add_u64 v[164:165], v[196:197], 0, s[38:39]
	s_mov_b32 m0, s49
	s_nop 0
	global_load_lds_dwordx4 v[164:165], off
	v_lshl_add_u64 v[164:165], v[198:199], 0, s[38:39]
	s_mov_b32 m0, s50
	s_nop 0
	global_load_lds_dwordx4 v[164:165], off
	s_waitcnt vmcnt(8)
	s_waitcnt lgkmcnt(0)
	s_barrier
	s_setprio 1
	s_waitcnt lgkmcnt(0)
	v_mfma_f32_16x16x128_f8f6f4 v[94:97], v[0:7], v[220:227], v[94:97]
	v_mfma_f32_16x16x128_f8f6f4 v[90:93], v[8:15], v[220:227], v[90:93]
	v_mfma_f32_16x16x128_f8f6f4 v[78:81], v[0:7], v[228:235], v[78:81]
	v_mfma_f32_16x16x128_f8f6f4 v[74:77], v[8:15], v[228:235], v[74:77]
	v_mfma_f32_16x16x128_f8f6f4 v[62:65], v[0:7], v[236:243], v[62:65]
	v_mfma_f32_16x16x128_f8f6f4 v[58:61], v[8:15], v[236:243], v[58:61]
	v_mfma_f32_16x16x128_f8f6f4 v[46:49], v[0:7], v[244:251], v[46:49]
	v_mfma_f32_16x16x128_f8f6f4 v[42:45], v[8:15], v[244:251], v[42:45]
	s_setprio 0
	s_setprio 1
	v_mfma_f32_16x16x128_f8f6f4 v[86:89], v[16:23], v[220:227], v[86:89]
	v_mfma_f32_16x16x128_f8f6f4 v[82:85], v[24:31], v[220:227], v[82:85]
	v_mfma_f32_16x16x128_f8f6f4 v[70:73], v[16:23], v[228:235], v[70:73]
	v_mfma_f32_16x16x128_f8f6f4 v[66:69], v[24:31], v[228:235], v[66:69]
	v_mfma_f32_16x16x128_f8f6f4 v[54:57], v[16:23], v[236:243], v[54:57]
	v_mfma_f32_16x16x128_f8f6f4 v[50:53], v[24:31], v[236:243], v[50:53]
	v_mfma_f32_16x16x128_f8f6f4 v[38:41], v[16:23], v[244:251], v[38:41]
	v_mfma_f32_16x16x128_f8f6f4 v[34:37], v[24:31], v[244:251], v[34:37]
	s_setprio 0
	s_barrier
	s_add_i32 s54, s54, 2
	s_add_u32 s30, s30, 0x100
	s_addc_u32 s31, s31, 0
	s_add_u32 s52, s52, 0x100
	s_addc_u32 s53, s53, 0
	s_cmp_gt_u32 s54, 13
	s_cbranch_scc0 .LBB0_114
	v_lshl_add_u32 v0, s20, 8, v33
	v_ashrrev_i32_e32 v1, 31, v0
	v_lshl_add_u64 v[2:3], v[0:1], 3, s[8:9]
	global_load_dwordx2 v[220:221], v[2:3], off
	global_load_dwordx2 v[222:223], v[2:3], off offset:128
	global_load_dwordx2 v[224:225], v[2:3], off offset:256
	global_load_dwordx2 v[226:227], v[2:3], off offset:384
	global_load_dwordx2 v[228:229], v[2:3], off offset:1024
	global_load_dwordx2 v[230:231], v[2:3], off offset:1152
	global_load_dwordx2 v[232:233], v[2:3], off offset:1280
	global_load_dwordx2 v[234:235], v[2:3], off offset:1408
	s_and_b64 vcc, exec, s[14:15]
	s_cbranch_vccz .LBB0_117
	s_barrier

; #define PG8_STAGE(bufoff, gbase, voff) do { _Pragma("unroll") for (int _i = 0; _i < 2; ++_i) \
;         __builtin_amdgcn_global_load_lds((const unsigned*)((const char*)(gbase) + (voff)[_i]), (PG8_LAS unsigned*)(lds + (bufoff) + ldsw + _i * 8192), 16, 0, 0); } while (0)
; #define PG8_WAIT_V(n) asm volatile("s_waitcnt vmcnt(" #n ")" ::: "memory")
; #define PG8_WAIT_L(n) asm volatile("s_waitcnt lgkmcnt(" #n ")" ::: "memory")
; #define PG8_BAR __builtin_amdgcn_s_barrier()
; #define PG8_SCHED __builtin_amdgcn_sched_barrier(0)
; template <class Epi, class Sched, bool ALIGN_EPI = false, bool SP2 = false, bool FP8 = false>
; __device__ __forceinline__ void gemm_phase(PG8_LAS unsigned char* lds, const Gemm g, const Sched& S, const Epi& E, const int tid) {
;     ...
;             PG8_WAIT_V(8); PG8_WAIT_L(0); PG8_BAR; PG8_MMA(1, 0, At, B0); PG8_MMA(1, 1, At, B1); PG8_BAR; PG8_SCHED;
;             PG8_LDB(B0, 1, 0); PG8_LDB(B1, 1, 1); PG8_SCHED; PG8_LDA(At, 1, 0); PG8_STAGE(PG8_SA(0, 1), a2 + hstepA, voffA);
;             PG8_WAIT_V(8); PG8_WAIT_L(0); PG8_BAR; PG8_MMA(0, 0, At, B0); PG8_MMA(0, 1, At, B1); PG8_BAR; PG8_SCHED;
.Lskw_2_1:
	s_waitcnt lgkmcnt(0)
	s_barrier
	s_setprio 1
	s_waitcnt lgkmcnt(0)
	s_nop 0
	v_mfma_f32_16x16x32_bf16 v[62:65], v[130:133], v[192:195], v[62:65]
	v_mfma_f32_16x16x32_bf16 v[58:61], v[138:141], v[192:195], v[58:61]
	v_mfma_f32_16x16x32_bf16 v[54:57], v[130:133], v[224:227], v[54:57]
	v_mfma_f32_16x16x32_bf16 v[50:53], v[138:141], v[224:227], v[50:53]
	v_mfma_f32_16x16x32_bf16 v[46:49], v[130:133], v[232:235], v[46:49]
	v_mfma_f32_16x16x32_bf16 v[42:45], v[138:141], v[232:235], v[42:45]
	v_mfma_f32_16x16x32_bf16 v[38:41], v[130:133], v[240:243], v[38:41]
	v_mfma_f32_16x16x32_bf16 v[34:37], v[138:141], v[240:243], v[34:37]
	v_mfma_f32_16x16x32_bf16 v[62:65], v[134:137], v[220:223], v[62:65]
	v_mfma_f32_16x16x32_bf16 v[58:61], v[142:145], v[220:223], v[58:61]
	v_mfma_f32_16x16x32_bf16 v[54:57], v[134:137], v[228:231], v[54:57]
	v_mfma_f32_16x16x32_bf16 v[50:53], v[142:145], v[228:231], v[50:53]
	v_mfma_f32_16x16x32_bf16 v[46:49], v[134:137], v[236:239], v[46:49]
	v_mfma_f32_16x16x32_bf16 v[42:45], v[142:145], v[236:239], v[42:45]
	v_mfma_f32_16x16x32_bf16 v[38:41], v[134:137], v[244:247], v[38:41]
	v_mfma_f32_16x16x32_bf16 v[34:37], v[142:145], v[244:247], v[34:37]
	s_setprio 0
	s_setprio 1
	v_mfma_f32_16x16x32_bf16 v[28:31], v[146:149], v[192:195], v[28:31]
	v_mfma_f32_16x16x32_bf16 v[24:27], v[154:157], v[192:195], v[24:27]
	v_mfma_f32_16x16x32_bf16 v[20:23], v[146:149], v[224:227], v[20:23]
	v_mfma_f32_16x16x32_bf16 v[16:19], v[154:157], v[224:227], v[16:19]
	v_mfma_f32_16x16x32_bf16 v[12:15], v[146:149], v[232:235], v[12:15]
	v_mfma_f32_16x16x32_bf16 v[8:11], v[154:157], v[232:235], v[8:11]
	v_mfma_f32_16x16x32_bf16 v[4:7], v[146:149], v[240:243], v[4:7]
	v_mfma_f32_16x16x32_bf16 v[0:3], v[154:157], v[240:243], v[0:3]
	v_mfma_f32_16x16x32_bf16 v[28:31], v[150:153], v[220:223], v[28:31]
	v_mfma_f32_16x16x32_bf16 v[24:27], v[158:161], v[220:223], v[24:27]
	v_mfma_f32_16x16x32_bf16 v[20:23], v[150:153], v[228:231], v[20:23]
	v_mfma_f32_16x16x32_bf16 v[16:19], v[158:161], v[228:231], v[16:19]
	v_mfma_f32_16x16x32_bf16 v[12:15], v[150:153], v[236:239], v[12:15]
	v_mfma_f32_16x16x32_bf16 v[8:11], v[158:161], v[236:239], v[8:11]
	v_mfma_f32_16x16x32_bf16 v[4:7], v[150:153], v[244:247], v[4:7]
	v_mfma_f32_16x16x32_bf16 v[0:3], v[158:161], v[244:247], v[0:3]
	s_setprio 0
	s_barrier
	s_add_i32 s61, 0, 0x18000
	s_add_i32 s62, 0, 0x1c000
	v_add_u32_e32 v142, s61, v163
	v_add_u32_e32 v158, s62, v163
	ds_read_b128 v[130:133], v142
	ds_read_b128 v[134:137], v142 offset:1024
	ds_read_b128 v[138:141], v142 offset:2048
	ds_read_b128 v[142:145], v142 offset:3072
	ds_read_b128 v[146:149], v158
	ds_read_b128 v[150:153], v158 offset:1024
	ds_read_b128 v[154:157], v158 offset:2048
	ds_read_b128 v[158:161], v158 offset:3072
	s_add_u32 s8, s36, 0x3c0000
	s_addc_u32 s9, s37, 0
	s_mov_b32 m0, s48
	v_lshl_add_u64 v[248:249], s[8:9], 0, v[186:187]
	ds_read_b128 v[192:195], v198 offset:32768
	ds_read_b128 v[220:223], v198 offset:33792
	ds_read_b128 v[224:227], v198 offset:34816
	ds_read_b128 v[228:231], v198 offset:35840
	ds_read_b128 v[232:235], v198 offset:36864
	ds_read_b128 v[236:239], v198 offset:37888
	ds_read_b128 v[240:243], v198 offset:38912
	ds_read_b128 v[244:247], v198 offset:39936
	global_load_lds_dwordx4 v[248:249], off
	v_lshl_add_u64 v[248:249], s[8:9], 0, v[182:183]
	s_mov_b32 m0, s49
	s_nop 0
	global_load_lds_dwordx4 v[248:249], off
	s_waitcnt vmcnt(8)
	s_waitcnt lgkmcnt(0)
	s_barrier
	s_setprio 1
	s_waitcnt lgkmcnt(0)
	s_nop 0
	v_mfma_f32_16x16x32_bf16 v[126:129], v[130:133], v[192:195], v[126:129]
	v_mfma_f32_16x16x32_bf16 v[122:125], v[138:141], v[192:195], v[122:125]
	v_mfma_f32_16x16x32_bf16 v[118:121], v[130:133], v[224:227], v[118:121]
	v_mfma_f32_16x16x32_bf16 v[114:117], v[138:141], v[224:227], v[114:117]
	v_mfma_f32_16x16x32_bf16 v[110:113], v[130:133], v[232:235], v[110:113]
	v_mfma_f32_16x16x32_bf16 v[106:109], v[138:141], v[232:235], v[106:109]
	v_mfma_f32_16x16x32_bf16 v[102:105], v[130:133], v[240:243], v[102:105]
	v_mfma_f32_16x16x32_bf16 v[98:101], v[138:141], v[240:243], v[98:101]
	v_mfma_f32_16x16x32_bf16 v[126:129], v[134:137], v[220:223], v[126:129]
	v_mfma_f32_16x16x32_bf16 v[122:125], v[142:145], v[220:223], v[122:125]
	v_mfma_f32_16x16x32_bf16 v[118:121], v[134:137], v[228:231], v[118:121]
	v_mfma_f32_16x16x32_bf16 v[114:117], v[142:145], v[228:231], v[114:117]
	v_mfma_f32_16x16x32_bf16 v[110:113], v[134:137], v[236:239], v[110:113]
	v_mfma_f32_16x16x32_bf16 v[106:109], v[142:145], v[236:239], v[106:109]
	v_mfma_f32_16x16x32_bf16 v[102:105], v[134:137], v[244:247], v[102:105]
	v_mfma_f32_16x16x32_bf16 v[98:101], v[142:145], v[244:247], v[98:101]
	s_setprio 0
	s_setprio 1
	v_mfma_f32_16x16x32_bf16 v[94:97], v[146:149], v[192:195], v[94:97]
	v_mfma_f32_16x16x32_bf16 v[90:93], v[154:157], v[192:195], v[90:93]
	v_mfma_f32_16x16x32_bf16 v[86:89], v[146:149], v[224:227], v[86:89]
	v_mfma_f32_16x16x32_bf16 v[82:85], v[154:157], v[224:227], v[82:85]
	v_mfma_f32_16x16x32_bf16 v[78:81], v[146:149], v[232:235], v[78:81]
	v_mfma_f32_16x16x32_bf16 v[74:77], v[154:157], v[232:235], v[74:77]
	v_mfma_f32_16x16x32_bf16 v[70:73], v[146:149], v[240:243], v[70:73]
	v_mfma_f32_16x16x32_bf16 v[66:69], v[154:157], v[240:243], v[66:69]
	v_mfma_f32_16x16x32_bf16 v[94:97], v[150:153], v[220:223], v[94:97]
	v_mfma_f32_16x16x32_bf16 v[90:93], v[158:161], v[220:223], v[90:93]
	v_mfma_f32_16x16x32_bf16 v[86:89], v[150:153], v[228:231], v[86:89]
	v_mfma_f32_16x16x32_bf16 v[82:85], v[158:161], v[228:231], v[82:85]
	v_mfma_f32_16x16x32_bf16 v[78:81], v[150:153], v[236:239], v[78:81]
	v_mfma_f32_16x16x32_bf16 v[74:77], v[158:161], v[236:239], v[74:77]
	v_mfma_f32_16x16x32_bf16 v[70:73], v[150:153], v[244:247], v[70:73]
	v_mfma_f32_16x16x32_bf16 v[66:69], v[158:161], v[244:247], v[66:69]
	s_setprio 0
	s_barrier
; #define PG8_STAGE(bufoff, gbase, voff) do { _Pragma("unroll") for (int _i = 0; _i < 2; ++_i) \
;         __builtin_amdgcn_global_load_lds((const unsigned*)((const char*)(gbase) + (voff)[_i]), (PG8_LAS unsigned*)(lds + (bufoff) + ldsw + _i * 8192), 16, 0, 0); } while (0)
; #define PG8_WAIT_V(n) asm volatile("s_waitcnt vmcnt(" #n ")" ::: "memory")
; #define PG8_WAIT_L(n) asm volatile("s_waitcnt lgkmcnt(" #n ")" ::: "memory")
; #define PG8_BAR __builtin_amdgcn_s_barrier()
; #define PG8_SCHED __builtin_amdgcn_sched_barrier(0)
; template <class Epi, class Sched, bool ALIGN_EPI = false, bool SP2 = false, bool FP8 = false>
; __device__ __forceinline__ void gemm_phase(PG8_LAS unsigned char* lds, const Gemm g, const Sched& S, const Epi& E, const int tid) {
;     ...
;             PG8_LDA(At, 1, 1); PG8_STAGE(PG8_SB(1, 0), b3, voffB); PG8_STAGE(PG8_SB(1, 1), b3 + hstepB, voffB); PG8_STAGE(PG8_SA(1, 0), a3, voffA);
;             PG8_WAIT_V(8); PG8_WAIT_L(0); PG8_BAR; PG8_MMA(1, 0, At, B0); PG8_MMA(1, 1, At, B1); PG8_BAR; PG8_SCHED;
	s_add_i32 s8, s61, s45
	v_lshl_add_u64 v[164:165], v[164:165], 0, s[38:39]
	s_mov_b32 m0, s8
	ds_read_b128 v[192:195], v198 offset:49152
	ds_read_b128 v[220:223], v198 offset:50176
	ds_read_b128 v[224:227], v198 offset:51200
	ds_read_b128 v[228:231], v198 offset:52224
	ds_read_b128 v[232:235], v198 offset:53248
	ds_read_b128 v[236:239], v198 offset:54272
	ds_read_b128 v[240:243], v198 offset:55296
	ds_read_b128 v[244:247], v198 offset:56320
	global_load_lds_dwordx4 v[164:165], off
	s_add_i32 m0, s8, 0x2000
	s_add_u32 s8, s34, 0x40080
	v_lshl_add_u64 v[164:165], v[166:167], 0, s[38:39]
	s_addc_u32 s9, s35, 0
	s_add_i32 s34, s62, s45
	global_load_lds_dwordx4 v[164:165], off
	v_lshl_add_u64 v[164:165], s[8:9], 0, v[184:185]
	s_mov_b32 m0, s34
	s_nop 0
	global_load_lds_dwordx4 v[164:165], off
	v_lshl_add_u64 v[164:165], s[8:9], 0, v[180:181]
	s_add_i32 m0, s34, 0x2000
	s_nop 0
	global_load_lds_dwordx4 v[164:165], off
	v_lshl_add_u64 v[164:165], v[196:197], 0, s[38:39]
	s_mov_b32 m0, s52
	s_nop 0
	global_load_lds_dwordx4 v[164:165], off
	v_lshl_add_u64 v[164:165], v[200:201], 0, s[38:39]
	s_mov_b32 m0, s53
	s_nop 0
	global_load_lds_dwordx4 v[164:165], off
	s_waitcnt vmcnt(8)
	s_waitcnt lgkmcnt(0)
	s_barrier
	s_setprio 1
	s_waitcnt lgkmcnt(0)
	v_mfma_f32_16x16x32_bf16 v[62:65], v[130:133], v[192:195], v[62:65]
	v_mfma_f32_16x16x32_bf16 v[58:61], v[138:141], v[192:195], v[58:61]
	v_mfma_f32_16x16x32_bf16 v[54:57], v[130:133], v[224:227], v[54:57]
	v_mfma_f32_16x16x32_bf16 v[50:53], v[138:141], v[224:227], v[50:53]
	v_mfma_f32_16x16x32_bf16 v[46:49], v[130:133], v[232:235], v[46:49]
	v_mfma_f32_16x16x32_bf16 v[42:45], v[138:141], v[232:235], v[42:45]
	v_mfma_f32_16x16x32_bf16 v[38:41], v[130:133], v[240:243], v[38:41]
	v_mfma_f32_16x16x32_bf16 v[34:37], v[138:141], v[240:243], v[34:37]
	v_mfma_f32_16x16x32_bf16 v[62:65], v[134:137], v[220:223], v[62:65]
	v_mfma_f32_16x16x32_bf16 v[58:61], v[142:145], v[220:223], v[58:61]
	v_mfma_f32_16x16x32_bf16 v[54:57], v[134:137], v[228:231], v[54:57]
	v_mfma_f32_16x16x32_bf16 v[50:53], v[142:145], v[228:231], v[50:53]
	v_mfma_f32_16x16x32_bf16 v[46:49], v[134:137], v[236:239], v[46:49]
	v_mfma_f32_16x16x32_bf16 v[42:45], v[142:145], v[236:239], v[42:45]
	v_mfma_f32_16x16x32_bf16 v[38:41], v[134:137], v[244:247], v[38:41]
	v_mfma_f32_16x16x32_bf16 v[34:37], v[142:145], v[244:247], v[34:37]
	s_setprio 0
	s_setprio 1
	v_mfma_f32_16x16x32_bf16 v[28:31], v[146:149], v[192:195], v[28:31]
	v_mfma_f32_16x16x32_bf16 v[24:27], v[154:157], v[192:195], v[24:27]
	v_mfma_f32_16x16x32_bf16 v[20:23], v[146:149], v[224:227], v[20:23]
	v_mfma_f32_16x16x32_bf16 v[16:19], v[154:157], v[224:227], v[16:19]
	v_mfma_f32_16x16x32_bf16 v[12:15], v[146:149], v[232:235], v[12:15]
	v_mfma_f32_16x16x32_bf16 v[8:11], v[154:157], v[232:235], v[8:11]
	v_mfma_f32_16x16x32_bf16 v[4:7], v[146:149], v[240:243], v[4:7]
	v_mfma_f32_16x16x32_bf16 v[0:3], v[154:157], v[240:243], v[0:3]
	v_mfma_f32_16x16x32_bf16 v[28:31], v[150:153], v[220:223], v[28:31]
	v_mfma_f32_16x16x32_bf16 v[24:27], v[158:161], v[220:223], v[24:27]
	v_mfma_f32_16x16x32_bf16 v[20:23], v[150:153], v[228:231], v[20:23]
	v_mfma_f32_16x16x32_bf16 v[16:19], v[158:161], v[228:231], v[16:19]
	v_mfma_f32_16x16x32_bf16 v[12:15], v[150:153], v[236:239], v[12:15]
	v_mfma_f32_16x16x32_bf16 v[8:11], v[158:161], v[236:239], v[8:11]
	v_mfma_f32_16x16x32_bf16 v[4:7], v[150:153], v[244:247], v[4:7]
	v_mfma_f32_16x16x32_bf16 v[0:3], v[158:161], v[244:247], v[0:3]
	s_setprio 0
	s_barrier
	s_add_u32 s58, s58, 0x100
	s_addc_u32 s59, s59, 0
	s_cmp_ge_u32 s60, s27
	s_mov_b64 s[8:9], s[6:7]
	s_mov_b32 s36, s60
	s_cbranch_scc0 .LBB0_457
	s_and_b64 vcc, exec, s[24:25]
	s_cbranch_vccz .LBB0_460
	s_barrier

; #define PG8_STAGE(bufoff, gbase, voff) do { _Pragma("unroll") for (int _i = 0; _i < 2; ++_i) \
;         __builtin_amdgcn_global_load_lds((const unsigned*)((const char*)(gbase) + (voff)[_i]), (PG8_LAS unsigned*)(lds + (bufoff) + ldsw + _i * 8192), 16, 0, 0); } while (0)
; #define PG8_WAIT_V(n) asm volatile("s_waitcnt vmcnt(" #n ")" ::: "memory")
; #define PG8_WAIT_L(n) asm volatile("s_waitcnt lgkmcnt(" #n ")" ::: "memory")
; #define PG8_BAR __builtin_amdgcn_s_barrier()
; #define PG8_SCHED __builtin_amdgcn_sched_barrier(0)
; template <class Epi, class Sched, bool ALIGN_EPI = false, bool SP2 = false, bool FP8 = false>
; __device__ __forceinline__ void gemm_phase(PG8_LAS unsigned char* lds, const Gemm g, const Sched& S, const Epi& E, const int tid) {
;     ...
;             PG8_WAIT_V(8); PG8_WAIT_L(0); PG8_BAR; PG8_MMA(0, 0, At, B0); PG8_MMA(0, 1, At, B1); PG8_BAR; PG8_SCHED;
;             PG8_LDA(At, 0, 1); PG8_STAGE(PG8_SB(0, 0), b2, voffB); PG8_STAGE(PG8_SB(0, 1), b2 + hstepB, voffB); PG8_STAGE(PG8_SA(0, 0), a2, voffA);
;             PG8_WAIT_V(8); PG8_WAIT_L(0); PG8_BAR; PG8_MMA(1, 0, At, B0); PG8_MMA(1, 1, At, B1); PG8_BAR; PG8_SCHED;
.Lskw_3_0:
	s_waitcnt lgkmcnt(0)
	s_barrier
	s_setprio 1
	s_waitcnt lgkmcnt(0)
	s_nop 0
	v_mfma_f32_16x16x32_bf16 v[126:129], v[130:133], v[192:195], v[126:129]
	v_mfma_f32_16x16x32_bf16 v[122:125], v[138:141], v[192:195], v[122:125]
	v_mfma_f32_16x16x32_bf16 v[110:113], v[130:133], v[222:225], v[110:113]
	v_mfma_f32_16x16x32_bf16 v[106:109], v[138:141], v[222:225], v[106:109]
	v_mfma_f32_16x16x32_bf16 v[94:97], v[130:133], v[230:233], v[94:97]
	v_mfma_f32_16x16x32_bf16 v[90:93], v[138:141], v[230:233], v[90:93]
	v_mfma_f32_16x16x32_bf16 v[78:81], v[130:133], v[238:241], v[78:81]
	v_mfma_f32_16x16x32_bf16 v[74:77], v[138:141], v[238:241], v[74:77]
	v_mfma_f32_16x16x32_bf16 v[126:129], v[134:137], v[196:199], v[126:129]
	v_mfma_f32_16x16x32_bf16 v[122:125], v[142:145], v[196:199], v[122:125]
	v_mfma_f32_16x16x32_bf16 v[110:113], v[134:137], v[226:229], v[110:113]
	v_mfma_f32_16x16x32_bf16 v[106:109], v[142:145], v[226:229], v[106:109]
	v_mfma_f32_16x16x32_bf16 v[94:97], v[134:137], v[234:237], v[94:97]
	v_mfma_f32_16x16x32_bf16 v[90:93], v[142:145], v[234:237], v[90:93]
	v_mfma_f32_16x16x32_bf16 v[78:81], v[134:137], v[242:245], v[78:81]
	v_mfma_f32_16x16x32_bf16 v[74:77], v[142:145], v[242:245], v[74:77]
	s_setprio 0
	s_setprio 1
	v_mfma_f32_16x16x32_bf16 v[118:121], v[146:149], v[192:195], v[118:121]
	v_mfma_f32_16x16x32_bf16 v[114:117], v[154:157], v[192:195], v[114:117]
	v_mfma_f32_16x16x32_bf16 v[102:105], v[146:149], v[222:225], v[102:105]
	v_mfma_f32_16x16x32_bf16 v[98:101], v[154:157], v[222:225], v[98:101]
	v_mfma_f32_16x16x32_bf16 v[86:89], v[146:149], v[230:233], v[86:89]
	v_mfma_f32_16x16x32_bf16 v[82:85], v[154:157], v[230:233], v[82:85]
	v_mfma_f32_16x16x32_bf16 v[70:73], v[146:149], v[238:241], v[70:73]
	v_mfma_f32_16x16x32_bf16 v[66:69], v[154:157], v[238:241], v[66:69]
	v_mfma_f32_16x16x32_bf16 v[118:121], v[150:153], v[196:199], v[118:121]
	v_mfma_f32_16x16x32_bf16 v[114:117], v[158:161], v[196:199], v[114:117]
	v_mfma_f32_16x16x32_bf16 v[102:105], v[150:153], v[226:229], v[102:105]
	v_mfma_f32_16x16x32_bf16 v[98:101], v[158:161], v[226:229], v[98:101]
	v_mfma_f32_16x16x32_bf16 v[86:89], v[150:153], v[234:237], v[86:89]
	v_mfma_f32_16x16x32_bf16 v[82:85], v[158:161], v[234:237], v[82:85]
	v_mfma_f32_16x16x32_bf16 v[70:73], v[150:153], v[242:245], v[70:73]
	v_mfma_f32_16x16x32_bf16 v[66:69], v[158:161], v[242:245], v[66:69]
	s_setprio 0
	s_barrier
	s_add_i32 s63, s63, s52
	v_lshl_add_u64 v[164:165], s[44:45], 0, v[184:185]
	s_mov_b32 m0, s63
	ds_read_b128 v[192:195], v220 offset:16384
	ds_read_b128 v[196:199], v220 offset:17408
	ds_read_b128 v[222:225], v220 offset:18432
	ds_read_b128 v[226:229], v220 offset:19456
	ds_read_b128 v[230:233], v220 offset:20480
	ds_read_b128 v[234:237], v220 offset:21504
	ds_read_b128 v[238:241], v220 offset:22528
	ds_read_b128 v[242:245], v220 offset:23552
	global_load_lds_dwordx4 v[164:165], off
	s_add_i32 m0, s63, 0x2000
	s_add_u32 s64, s44, 0x80000
	v_lshl_add_u64 v[166:167], s[44:45], 0, v[180:181]
	s_addc_u32 s65, s45, 0
	s_add_i32 s63, s66, s52
	global_load_lds_dwordx4 v[166:167], off
	v_lshl_add_u64 v[200:201], s[64:65], 0, v[184:185]
	s_mov_b32 m0, s63
	v_lshl_add_u64 v[246:247], s[46:47], 0, v[182:183]
	global_load_lds_dwordx4 v[200:201], off
	v_lshl_add_u64 v[200:201], s[64:65], 0, v[180:181]
	s_add_i32 m0, s63, 0x2000
	s_nop 0
	global_load_lds_dwordx4 v[200:201], off
	v_lshl_add_u64 v[200:201], s[46:47], 0, v[186:187]
	s_mov_b32 m0, s53
	s_nop 0
	global_load_lds_dwordx4 v[200:201], off
	s_mov_b32 m0, s54
	s_nop 0
	global_load_lds_dwordx4 v[246:247], off
	s_cmp_eq_i32 s62, -2
	s_cbranch_scc1 .Lskw_3_1
	s_waitcnt vmcnt(8)
.Lskw_3_1:
	s_waitcnt lgkmcnt(0)
	s_barrier
	s_setprio 1
	s_waitcnt lgkmcnt(0)
	s_nop 0
	v_mfma_f32_16x16x32_bf16 v[62:65], v[130:133], v[192:195], v[62:65]
	v_mfma_f32_16x16x32_bf16 v[58:61], v[138:141], v[192:195], v[58:61]
	v_mfma_f32_16x16x32_bf16 v[46:49], v[130:133], v[222:225], v[46:49]
	v_mfma_f32_16x16x32_bf16 v[42:45], v[138:141], v[222:225], v[42:45]
	v_mfma_f32_16x16x32_bf16 v[28:31], v[130:133], v[230:233], v[28:31]
	v_mfma_f32_16x16x32_bf16 v[24:27], v[138:141], v[230:233], v[24:27]
	v_mfma_f32_16x16x32_bf16 v[12:15], v[130:133], v[238:241], v[12:15]
	v_mfma_f32_16x16x32_bf16 v[8:11], v[138:141], v[238:241], v[8:11]
	v_mfma_f32_16x16x32_bf16 v[62:65], v[134:137], v[196:199], v[62:65]
	v_mfma_f32_16x16x32_bf16 v[58:61], v[142:145], v[196:199], v[58:61]
	v_mfma_f32_16x16x32_bf16 v[46:49], v[134:137], v[226:229], v[46:49]
	v_mfma_f32_16x16x32_bf16 v[42:45], v[142:145], v[226:229], v[42:45]
	v_mfma_f32_16x16x32_bf16 v[28:31], v[134:137], v[234:237], v[28:31]
	v_mfma_f32_16x16x32_bf16 v[24:27], v[142:145], v[234:237], v[24:27]
	v_mfma_f32_16x16x32_bf16 v[12:15], v[134:137], v[242:245], v[12:15]
	v_mfma_f32_16x16x32_bf16 v[8:11], v[142:145], v[242:245], v[8:11]
	s_setprio 0
	s_setprio 1
	v_mfma_f32_16x16x32_bf16 v[54:57], v[146:149], v[192:195], v[54:57]
	v_mfma_f32_16x16x32_bf16 v[50:53], v[154:157], v[192:195], v[50:53]
	v_mfma_f32_16x16x32_bf16 v[38:41], v[146:149], v[222:225], v[38:41]
	v_mfma_f32_16x16x32_bf16 v[34:37], v[154:157], v[222:225], v[34:37]
	v_mfma_f32_16x16x32_bf16 v[20:23], v[146:149], v[230:233], v[20:23]
	v_mfma_f32_16x16x32_bf16 v[16:19], v[154:157], v[230:233], v[16:19]
	v_mfma_f32_16x16x32_bf16 v[4:7], v[146:149], v[238:241], v[4:7]
	v_mfma_f32_16x16x32_bf16 v[0:3], v[154:157], v[238:241], v[0:3]
	v_mfma_f32_16x16x32_bf16 v[54:57], v[150:153], v[196:199], v[54:57]
	v_mfma_f32_16x16x32_bf16 v[50:53], v[158:161], v[196:199], v[50:53]
	v_mfma_f32_16x16x32_bf16 v[38:41], v[150:153], v[226:229], v[38:41]
	v_mfma_f32_16x16x32_bf16 v[34:37], v[158:161], v[226:229], v[34:37]
	v_mfma_f32_16x16x32_bf16 v[20:23], v[150:153], v[234:237], v[20:23]
	v_mfma_f32_16x16x32_bf16 v[16:19], v[158:161], v[234:237], v[16:19]
	v_mfma_f32_16x16x32_bf16 v[4:7], v[150:153], v[242:245], v[4:7]
	v_mfma_f32_16x16x32_bf16 v[0:3], v[158:161], v[242:245], v[0:3]
	s_setprio 0
	s_barrier
; #define PG8_STAGE(bufoff, gbase, voff) do { _Pragma("unroll") for (int _i = 0; _i < 2; ++_i) \
;         __builtin_amdgcn_global_load_lds((const unsigned*)((const char*)(gbase) + (voff)[_i]), (PG8_LAS unsigned*)(lds + (bufoff) + ldsw + _i * 8192), 16, 0, 0); } while (0)
; #define PG8_WAIT_V(n) asm volatile("s_waitcnt vmcnt(" #n ")" ::: "memory")
; #define PG8_WAIT_L(n) asm volatile("s_waitcnt lgkmcnt(" #n ")" ::: "memory")
; #define PG8_BAR __builtin_amdgcn_s_barrier()
; #define PG8_SCHED __builtin_amdgcn_sched_barrier(0)
; template <class Epi, class Sched, bool ALIGN_EPI = false, bool SP2 = false, bool FP8 = false>
; __device__ __forceinline__ void gemm_phase(PG8_LAS unsigned char* lds, const Gemm g, const Sched& S, const Epi& E, const int tid) {
;     ...
;             PG8_LDB(B0, 1, 0); PG8_LDB(B1, 1, 1); PG8_SCHED; PG8_LDA(At, 1, 0); PG8_STAGE(PG8_SA(0, 1), a2 + hstepA, voffA);
;             PG8_WAIT_V(8); PG8_WAIT_L(0); PG8_BAR; PG8_MMA(0, 0, At, B0); PG8_MMA(0, 1, At, B1); PG8_BAR; PG8_SCHED;
	s_add_i32 s63, 0, 0x18000
	s_add_i32 s64, 0, 0x1c000
	v_add_u32_e32 v142, s63, v163
	v_add_u32_e32 v158, s64, v163
	ds_read_b128 v[130:133], v142
	ds_read_b128 v[134:137], v142 offset:1024
	ds_read_b128 v[138:141], v142 offset:2048
	ds_read_b128 v[142:145], v142 offset:3072
	ds_read_b128 v[146:149], v158
	ds_read_b128 v[150:153], v158 offset:1024
	ds_read_b128 v[154:157], v158 offset:2048
	ds_read_b128 v[158:161], v158 offset:3072
	s_add_u32 s46, s46, 0x80000
	s_addc_u32 s47, s47, 0
	s_mov_b32 m0, s55
	v_lshl_add_u64 v[248:249], s[46:47], 0, v[186:187]
	ds_read_b128 v[192:195], v220 offset:32768
	ds_read_b128 v[196:199], v220 offset:33792
	ds_read_b128 v[222:225], v220 offset:34816
	ds_read_b128 v[226:229], v220 offset:35840
	ds_read_b128 v[230:233], v220 offset:36864
	ds_read_b128 v[234:237], v220 offset:37888
	ds_read_b128 v[238:241], v220 offset:38912
	ds_read_b128 v[242:245], v220 offset:39936
	global_load_lds_dwordx4 v[248:249], off
	v_lshl_add_u64 v[248:249], s[46:47], 0, v[182:183]
	s_mov_b32 m0, s56
	s_nop 0
	global_load_lds_dwordx4 v[248:249], off
	s_waitcnt vmcnt(8)
	s_waitcnt lgkmcnt(0)
	s_barrier
	s_setprio 1
	s_waitcnt lgkmcnt(0)
	s_nop 0
	v_mfma_f32_16x16x32_bf16 v[126:129], v[130:133], v[192:195], v[126:129]
	v_mfma_f32_16x16x32_bf16 v[122:125], v[138:141], v[192:195], v[122:125]
	v_mfma_f32_16x16x32_bf16 v[110:113], v[130:133], v[222:225], v[110:113]
	v_mfma_f32_16x16x32_bf16 v[106:109], v[138:141], v[222:225], v[106:109]
	v_mfma_f32_16x16x32_bf16 v[94:97], v[130:133], v[230:233], v[94:97]
	v_mfma_f32_16x16x32_bf16 v[90:93], v[138:141], v[230:233], v[90:93]
	v_mfma_f32_16x16x32_bf16 v[78:81], v[130:133], v[238:241], v[78:81]
	v_mfma_f32_16x16x32_bf16 v[74:77], v[138:141], v[238:241], v[74:77]
	v_mfma_f32_16x16x32_bf16 v[126:129], v[134:137], v[196:199], v[126:129]
	v_mfma_f32_16x16x32_bf16 v[122:125], v[142:145], v[196:199], v[122:125]
	v_mfma_f32_16x16x32_bf16 v[110:113], v[134:137], v[226:229], v[110:113]
	v_mfma_f32_16x16x32_bf16 v[106:109], v[142:145], v[226:229], v[106:109]
	v_mfma_f32_16x16x32_bf16 v[94:97], v[134:137], v[234:237], v[94:97]
	v_mfma_f32_16x16x32_bf16 v[90:93], v[142:145], v[234:237], v[90:93]
	v_mfma_f32_16x16x32_bf16 v[78:81], v[134:137], v[242:245], v[78:81]
	v_mfma_f32_16x16x32_bf16 v[74:77], v[142:145], v[242:245], v[74:77]
	s_setprio 0
	s_setprio 1
	v_mfma_f32_16x16x32_bf16 v[118:121], v[146:149], v[192:195], v[118:121]
	v_mfma_f32_16x16x32_bf16 v[114:117], v[154:157], v[192:195], v[114:117]
	v_mfma_f32_16x16x32_bf16 v[102:105], v[146:149], v[222:225], v[102:105]
	v_mfma_f32_16x16x32_bf16 v[98:101], v[154:157], v[222:225], v[98:101]
	v_mfma_f32_16x16x32_bf16 v[86:89], v[146:149], v[230:233], v[86:89]
	v_mfma_f32_16x16x32_bf16 v[82:85], v[154:157], v[230:233], v[82:85]
	v_mfma_f32_16x16x32_bf16 v[70:73], v[146:149], v[238:241], v[70:73]
	v_mfma_f32_16x16x32_bf16 v[66:69], v[154:157], v[238:241], v[66:69]
	v_mfma_f32_16x16x32_bf16 v[118:121], v[150:153], v[196:199], v[118:121]
	v_mfma_f32_16x16x32_bf16 v[114:117], v[158:161], v[196:199], v[114:117]
	v_mfma_f32_16x16x32_bf16 v[102:105], v[150:153], v[226:229], v[102:105]
	v_mfma_f32_16x16x32_bf16 v[98:101], v[158:161], v[226:229], v[98:101]
	v_mfma_f32_16x16x32_bf16 v[86:89], v[150:153], v[234:237], v[86:89]
	v_mfma_f32_16x16x32_bf16 v[82:85], v[158:161], v[234:237], v[82:85]
	v_mfma_f32_16x16x32_bf16 v[70:73], v[150:153], v[242:245], v[70:73]
	v_mfma_f32_16x16x32_bf16 v[66:69], v[158:161], v[242:245], v[66:69]
	s_setprio 0
	s_barrier
; #define PG8_STAGE(bufoff, gbase, voff) do { _Pragma("unroll") for (int _i = 0; _i < 2; ++_i) \
;         __builtin_amdgcn_global_load_lds((const unsigned*)((const char*)(gbase) + (voff)[_i]), (PG8_LAS unsigned*)(lds + (bufoff) + ldsw + _i * 8192), 16, 0, 0); } while (0)
; #define PG8_WAIT_V(n) asm volatile("s_waitcnt vmcnt(" #n ")" ::: "memory")
; #define PG8_WAIT_L(n) asm volatile("s_waitcnt lgkmcnt(" #n ")" ::: "memory")
; #define PG8_BAR __builtin_amdgcn_s_barrier()
; #define PG8_SCHED __builtin_amdgcn_sched_barrier(0)
; template <class Epi, class Sched, bool ALIGN_EPI = false, bool SP2 = false, bool FP8 = false>
; __device__ __forceinline__ void gemm_phase(PG8_LAS unsigned char* lds, const Gemm g, const Sched& S, const Epi& E, const int tid) {
;     ...
;             PG8_LDA(At, 1, 1); PG8_STAGE(PG8_SB(1, 0), b3, voffB); PG8_STAGE(PG8_SB(1, 1), b3 + hstepB, voffB); PG8_STAGE(PG8_SA(1, 0), a3, voffA);
;             PG8_WAIT_V(8); PG8_WAIT_L(0); PG8_BAR; PG8_MMA(1, 0, At, B0); PG8_MMA(1, 1, At, B1); PG8_BAR; PG8_SCHED;
	s_add_i32 s46, s63, s52
	v_lshl_add_u64 v[164:165], v[164:165], 0, s[38:39]
	s_mov_b32 m0, s46
	ds_read_b128 v[192:195], v220 offset:49152
	ds_read_b128 v[196:199], v220 offset:50176
	ds_read_b128 v[222:225], v220 offset:51200
	ds_read_b128 v[226:229], v220 offset:52224
	ds_read_b128 v[230:233], v220 offset:53248
	ds_read_b128 v[234:237], v220 offset:54272
	ds_read_b128 v[238:241], v220 offset:55296
	ds_read_b128 v[242:245], v220 offset:56320
	global_load_lds_dwordx4 v[164:165], off
	s_add_i32 m0, s46, 0x2000
	s_add_u32 s44, s44, 0x80080
	v_lshl_add_u64 v[164:165], v[166:167], 0, s[38:39]
	s_addc_u32 s45, s45, 0
	s_add_i32 s46, s64, s52
	global_load_lds_dwordx4 v[164:165], off
	v_lshl_add_u64 v[164:165], s[44:45], 0, v[184:185]
	s_mov_b32 m0, s46
	s_nop 0
	global_load_lds_dwordx4 v[164:165], off
	v_lshl_add_u64 v[164:165], s[44:45], 0, v[180:181]
	s_add_i32 m0, s46, 0x2000
	s_nop 0
	global_load_lds_dwordx4 v[164:165], off
	v_lshl_add_u64 v[164:165], v[200:201], 0, s[38:39]
	s_mov_b32 m0, s0
	s_nop 0
	global_load_lds_dwordx4 v[164:165], off
	v_lshl_add_u64 v[164:165], v[246:247], 0, s[38:39]
	s_mov_b32 m0, s57
	s_nop 0
	global_load_lds_dwordx4 v[164:165], off
	s_waitcnt vmcnt(8)
	s_waitcnt lgkmcnt(0)
	s_barrier
	s_setprio 1
	s_waitcnt lgkmcnt(0)
	v_mfma_f32_16x16x32_bf16 v[62:65], v[130:133], v[192:195], v[62:65]
	v_mfma_f32_16x16x32_bf16 v[58:61], v[138:141], v[192:195], v[58:61]
	v_mfma_f32_16x16x32_bf16 v[46:49], v[130:133], v[222:225], v[46:49]
	v_mfma_f32_16x16x32_bf16 v[42:45], v[138:141], v[222:225], v[42:45]
	v_mfma_f32_16x16x32_bf16 v[28:31], v[130:133], v[230:233], v[28:31]
	v_mfma_f32_16x16x32_bf16 v[24:27], v[138:141], v[230:233], v[24:27]
	v_mfma_f32_16x16x32_bf16 v[12:15], v[130:133], v[238:241], v[12:15]
	v_mfma_f32_16x16x32_bf16 v[8:11], v[138:141], v[238:241], v[8:11]
	v_mfma_f32_16x16x32_bf16 v[62:65], v[134:137], v[196:199], v[62:65]
	v_mfma_f32_16x16x32_bf16 v[58:61], v[142:145], v[196:199], v[58:61]
	v_mfma_f32_16x16x32_bf16 v[46:49], v[134:137], v[226:229], v[46:49]
	v_mfma_f32_16x16x32_bf16 v[42:45], v[142:145], v[226:229], v[42:45]
	v_mfma_f32_16x16x32_bf16 v[28:31], v[134:137], v[234:237], v[28:31]
	v_mfma_f32_16x16x32_bf16 v[24:27], v[142:145], v[234:237], v[24:27]
	v_mfma_f32_16x16x32_bf16 v[12:15], v[134:137], v[242:245], v[12:15]
	v_mfma_f32_16x16x32_bf16 v[8:11], v[142:145], v[242:245], v[8:11]
	s_setprio 0
	s_setprio 1
	v_mfma_f32_16x16x32_bf16 v[54:57], v[146:149], v[192:195], v[54:57]
	v_mfma_f32_16x16x32_bf16 v[50:53], v[154:157], v[192:195], v[50:53]
	v_mfma_f32_16x16x32_bf16 v[38:41], v[146:149], v[222:225], v[38:41]
	v_mfma_f32_16x16x32_bf16 v[34:37], v[154:157], v[222:225], v[34:37]
	v_mfma_f32_16x16x32_bf16 v[20:23], v[146:149], v[230:233], v[20:23]
	v_mfma_f32_16x16x32_bf16 v[16:19], v[154:157], v[230:233], v[16:19]
	v_mfma_f32_16x16x32_bf16 v[4:7], v[146:149], v[238:241], v[4:7]
	v_mfma_f32_16x16x32_bf16 v[0:3], v[154:157], v[238:241], v[0:3]
	v_mfma_f32_16x16x32_bf16 v[54:57], v[150:153], v[196:199], v[54:57]
	v_mfma_f32_16x16x32_bf16 v[50:53], v[158:161], v[196:199], v[50:53]
	v_mfma_f32_16x16x32_bf16 v[38:41], v[150:153], v[226:229], v[38:41]
	v_mfma_f32_16x16x32_bf16 v[34:37], v[158:161], v[226:229], v[34:37]
	v_mfma_f32_16x16x32_bf16 v[20:23], v[150:153], v[234:237], v[20:23]
	v_mfma_f32_16x16x32_bf16 v[16:19], v[158:161], v[234:237], v[16:19]
	v_mfma_f32_16x16x32_bf16 v[4:7], v[150:153], v[242:245], v[4:7]
	v_mfma_f32_16x16x32_bf16 v[0:3], v[158:161], v[242:245], v[0:3]
	s_setprio 0
	s_barrier
	s_add_i32 s62, s62, 2
	s_add_u32 s8, s8, 0x100
	s_addc_u32 s9, s9, 0
	s_add_u32 s60, s60, 0x100
	s_addc_u32 s61, s61, 0
	s_cmp_gt_u32 s62, 29
	s_cbranch_scc0 .LBB0_589
	s_and_b64 vcc, exec, s[26:27]
	s_cbranch_vccz .LBB0_592
	s_barrier

; #define PG8_STAGE(bufoff, gbase, voff) do { _Pragma("unroll") for (int _i = 0; _i < 2; ++_i) \
;         __builtin_amdgcn_global_load_lds((const unsigned*)((const char*)(gbase) + (voff)[_i]), (PG8_LAS unsigned*)(lds + (bufoff) + ldsw + _i * 8192), 16, 0, 0); } while (0)
; #define PG8_WAIT_V(n) asm volatile("s_waitcnt vmcnt(" #n ")" ::: "memory")
; #define PG8_WAIT_L(n) asm volatile("s_waitcnt lgkmcnt(" #n ")" ::: "memory")
; #define PG8_BAR __builtin_amdgcn_s_barrier()
; #define PG8_SCHED __builtin_amdgcn_sched_barrier(0)
; template <class Epi, class Sched, bool ALIGN_EPI = false, bool SP2 = false, bool FP8 = false>
; __device__ __forceinline__ void gemm_phase(PG8_LAS unsigned char* lds, const Gemm g, const Sched& S, const Epi& E, const int tid) {
;     ...
;             PG8_WAIT_V(8); PG8_WAIT_L(0); PG8_BAR; PG8_MMA(1, 0, At, B0); PG8_MMA(1, 1, At, B1); PG8_BAR; PG8_SCHED;
;             PG8_LDB(B0, 1, 0); PG8_LDB(B1, 1, 1); PG8_SCHED; PG8_LDA(At, 1, 0); PG8_STAGE(PG8_SA(0, 1), a2 + hstepA, voffA);
;             PG8_WAIT_V(8); PG8_WAIT_L(0); PG8_BAR; PG8_MMA(0, 0, At, B0); PG8_MMA(0, 1, At, B1); PG8_BAR; PG8_SCHED;
.Lskw_4_1:
	s_waitcnt lgkmcnt(0)
	s_barrier
	s_setprio 1
	s_waitcnt lgkmcnt(0)
	s_nop 0
	v_mfma_f32_16x16x32_bf16 v[62:65], v[142:145], v[196:199], v[62:65]
	v_mfma_f32_16x16x32_bf16 v[58:61], v[154:157], v[196:199], v[58:61]
	v_mfma_f32_16x16x32_bf16 v[46:49], v[142:145], v[224:227], v[46:49]
	v_mfma_f32_16x16x32_bf16 v[42:45], v[154:157], v[224:227], v[42:45]
	v_mfma_f32_16x16x32_bf16 v[28:31], v[142:145], v[232:235], v[28:31]
	v_mfma_f32_16x16x32_bf16 v[24:27], v[154:157], v[232:235], v[24:27]
	v_mfma_f32_16x16x32_bf16 v[12:15], v[142:145], v[240:243], v[12:15]
	v_mfma_f32_16x16x32_bf16 v[8:11], v[154:157], v[240:243], v[8:11]
	v_mfma_f32_16x16x32_bf16 v[62:65], v[146:149], v[220:223], v[62:65]
	v_mfma_f32_16x16x32_bf16 v[58:61], v[158:161], v[220:223], v[58:61]
	v_mfma_f32_16x16x32_bf16 v[46:49], v[146:149], v[228:231], v[46:49]
	v_mfma_f32_16x16x32_bf16 v[42:45], v[158:161], v[228:231], v[42:45]
	v_mfma_f32_16x16x32_bf16 v[28:31], v[146:149], v[236:239], v[28:31]
	v_mfma_f32_16x16x32_bf16 v[24:27], v[158:161], v[236:239], v[24:27]
	v_mfma_f32_16x16x32_bf16 v[12:15], v[146:149], v[244:247], v[12:15]
	v_mfma_f32_16x16x32_bf16 v[8:11], v[158:161], v[244:247], v[8:11]
	s_setprio 0
	s_setprio 1
	v_mfma_f32_16x16x32_bf16 v[54:57], v[180:183], v[196:199], v[54:57]
	v_mfma_f32_16x16x32_bf16 v[50:53], v[188:191], v[196:199], v[50:53]
	v_mfma_f32_16x16x32_bf16 v[38:41], v[180:183], v[224:227], v[38:41]
	v_mfma_f32_16x16x32_bf16 v[34:37], v[188:191], v[224:227], v[34:37]
	v_mfma_f32_16x16x32_bf16 v[20:23], v[180:183], v[232:235], v[20:23]
	v_mfma_f32_16x16x32_bf16 v[16:19], v[188:191], v[232:235], v[16:19]
	v_mfma_f32_16x16x32_bf16 v[4:7], v[180:183], v[240:243], v[4:7]
	v_mfma_f32_16x16x32_bf16 v[0:3], v[188:191], v[240:243], v[0:3]
	v_mfma_f32_16x16x32_bf16 v[54:57], v[184:187], v[220:223], v[54:57]
	v_mfma_f32_16x16x32_bf16 v[50:53], v[192:195], v[220:223], v[50:53]
	v_mfma_f32_16x16x32_bf16 v[38:41], v[184:187], v[228:231], v[38:41]
	v_mfma_f32_16x16x32_bf16 v[34:37], v[192:195], v[228:231], v[34:37]
	v_mfma_f32_16x16x32_bf16 v[20:23], v[184:187], v[236:239], v[20:23]
	v_mfma_f32_16x16x32_bf16 v[16:19], v[192:195], v[236:239], v[16:19]
	v_mfma_f32_16x16x32_bf16 v[4:7], v[184:187], v[244:247], v[4:7]
	v_mfma_f32_16x16x32_bf16 v[0:3], v[192:195], v[244:247], v[0:3]
	s_setprio 0
	s_barrier
	s_add_i32 s57, 0, 0x18000
	v_add_u32_e32 v153, s57, v150
	s_add_i32 s58, 0, 0x1c000
	ds_read_b128 v[142:145], v153
	ds_read_b128 v[146:149], v153 offset:1024
	ds_read_b128 v[154:157], v153 offset:2048
	ds_read_b128 v[158:161], v153 offset:3072
	v_add_u32_e32 v153, s58, v150
	ds_read_b128 v[180:183], v153
	ds_read_b128 v[184:187], v153 offset:1024
	ds_read_b128 v[188:191], v153 offset:2048
	ds_read_b128 v[192:195], v153 offset:3072
	s_add_u32 s36, s36, 0x80000
	s_addc_u32 s37, s37, 0
	s_mov_b32 m0, s49
	v_lshl_add_u64 v[250:251], s[36:37], 0, v[136:137]
	ds_read_b128 v[196:199], v152 offset:32768
	ds_read_b128 v[220:223], v152 offset:33792
	ds_read_b128 v[224:227], v152 offset:34816
	ds_read_b128 v[228:231], v152 offset:35840
	ds_read_b128 v[232:235], v152 offset:36864
	ds_read_b128 v[236:239], v152 offset:37888
	ds_read_b128 v[240:243], v152 offset:38912
	ds_read_b128 v[244:247], v152 offset:39936
	global_load_lds_dwordx4 v[250:251], off
	v_lshl_add_u64 v[250:251], s[36:37], 0, v[132:133]
	s_mov_b32 m0, s50
	s_nop 0
	global_load_lds_dwordx4 v[250:251], off
	s_waitcnt vmcnt(8)
	s_waitcnt lgkmcnt(0)
	s_barrier
	s_setprio 1
	s_waitcnt lgkmcnt(0)
	s_nop 0
	v_mfma_f32_16x16x32_bf16 v[126:129], v[142:145], v[196:199], v[126:129]
	v_mfma_f32_16x16x32_bf16 v[122:125], v[154:157], v[196:199], v[122:125]
	v_mfma_f32_16x16x32_bf16 v[110:113], v[142:145], v[224:227], v[110:113]
	v_mfma_f32_16x16x32_bf16 v[106:109], v[154:157], v[224:227], v[106:109]
	v_mfma_f32_16x16x32_bf16 v[94:97], v[142:145], v[232:235], v[94:97]
	v_mfma_f32_16x16x32_bf16 v[90:93], v[154:157], v[232:235], v[90:93]
	v_mfma_f32_16x16x32_bf16 v[78:81], v[142:145], v[240:243], v[78:81]
	v_mfma_f32_16x16x32_bf16 v[74:77], v[154:157], v[240:243], v[74:77]
	v_mfma_f32_16x16x32_bf16 v[126:129], v[146:149], v[220:223], v[126:129]
	v_mfma_f32_16x16x32_bf16 v[122:125], v[158:161], v[220:223], v[122:125]
	v_mfma_f32_16x16x32_bf16 v[110:113], v[146:149], v[228:231], v[110:113]
	v_mfma_f32_16x16x32_bf16 v[106:109], v[158:161], v[228:231], v[106:109]
	v_mfma_f32_16x16x32_bf16 v[94:97], v[146:149], v[236:239], v[94:97]
	v_mfma_f32_16x16x32_bf16 v[90:93], v[158:161], v[236:239], v[90:93]
	v_mfma_f32_16x16x32_bf16 v[78:81], v[146:149], v[244:247], v[78:81]
	v_mfma_f32_16x16x32_bf16 v[74:77], v[158:161], v[244:247], v[74:77]
	s_setprio 0
	s_setprio 1
	v_mfma_f32_16x16x32_bf16 v[118:121], v[180:183], v[196:199], v[118:121]
	v_mfma_f32_16x16x32_bf16 v[114:117], v[188:191], v[196:199], v[114:117]
	v_mfma_f32_16x16x32_bf16 v[102:105], v[180:183], v[224:227], v[102:105]
	v_mfma_f32_16x16x32_bf16 v[98:101], v[188:191], v[224:227], v[98:101]
	v_mfma_f32_16x16x32_bf16 v[86:89], v[180:183], v[232:235], v[86:89]
	v_mfma_f32_16x16x32_bf16 v[82:85], v[188:191], v[232:235], v[82:85]
	v_mfma_f32_16x16x32_bf16 v[70:73], v[180:183], v[240:243], v[70:73]
	v_mfma_f32_16x16x32_bf16 v[66:69], v[188:191], v[240:243], v[66:69]
	v_mfma_f32_16x16x32_bf16 v[118:121], v[184:187], v[220:223], v[118:121]
	v_mfma_f32_16x16x32_bf16 v[114:117], v[192:195], v[220:223], v[114:117]
	v_mfma_f32_16x16x32_bf16 v[102:105], v[184:187], v[228:231], v[102:105]
	v_mfma_f32_16x16x32_bf16 v[98:101], v[192:195], v[228:231], v[98:101]
	v_mfma_f32_16x16x32_bf16 v[86:89], v[184:187], v[236:239], v[86:89]
	v_mfma_f32_16x16x32_bf16 v[82:85], v[192:195], v[236:239], v[82:85]
	v_mfma_f32_16x16x32_bf16 v[70:73], v[184:187], v[244:247], v[70:73]
	v_mfma_f32_16x16x32_bf16 v[66:69], v[192:195], v[244:247], v[66:69]
	s_setprio 0
	s_barrier
; #define PG8_STAGE(bufoff, gbase, voff) do { _Pragma("unroll") for (int _i = 0; _i < 2; ++_i) \
;         __builtin_amdgcn_global_load_lds((const unsigned*)((const char*)(gbase) + (voff)[_i]), (PG8_LAS unsigned*)(lds + (bufoff) + ldsw + _i * 8192), 16, 0, 0); } while (0)
; #define PG8_WAIT_V(n) asm volatile("s_waitcnt vmcnt(" #n ")" ::: "memory")
; #define PG8_WAIT_L(n) asm volatile("s_waitcnt lgkmcnt(" #n ")" ::: "memory")
; #define PG8_BAR __builtin_amdgcn_s_barrier()
; #define PG8_SCHED __builtin_amdgcn_sched_barrier(0)
;     __device__ __forceinline__ void operator()(const f32x4 (&acc)[2][2][4][2], const Unit& u, int wr, int wc, int fr, int fq) const {
;     ...
;             for (int m = 0; m < 4; ++m) { const int row = row0 + ai * HALF + m * 16; const float rs = __builtin_amdgcn_rsqf((float)ss[row] * (SS_INV / 2048.0f) + RMS_EPS) * osc;
; template <class Epi, class Sched, bool ALIGN_EPI = false, bool SP2 = false, bool FP8 = false>
; __device__ __forceinline__ void gemm_phase(PG8_LAS unsigned char* lds, const Gemm g, const Sched& S, const Epi& E, const int tid) {
;     ...
;             PG8_LDA(At, 1, 1); PG8_STAGE(PG8_SB(1, 0), b3, voffB); PG8_STAGE(PG8_SB(1, 1), b3 + hstepB, voffB); PG8_STAGE(PG8_SA(1, 0), a3, voffA);
;             PG8_WAIT_V(8); PG8_WAIT_L(0); PG8_BAR; PG8_MMA(1, 0, At, B0); PG8_MMA(1, 1, At, B1); PG8_BAR; PG8_SCHED;
	s_add_i32 s36, s57, s46
	v_lshl_add_u64 v[164:165], v[164:165], 0, s[38:39]
	s_mov_b32 m0, s36
	ds_read_b128 v[196:199], v152 offset:49152
	ds_read_b128 v[220:223], v152 offset:50176
	ds_read_b128 v[224:227], v152 offset:51200
	ds_read_b128 v[228:231], v152 offset:52224
	ds_read_b128 v[232:235], v152 offset:53248
	ds_read_b128 v[236:239], v152 offset:54272
	ds_read_b128 v[240:243], v152 offset:55296
	ds_read_b128 v[244:247], v152 offset:56320
	global_load_lds_dwordx4 v[164:165], off
	s_add_i32 m0, s36, 0x2000
	s_add_u32 s34, s34, 0x80080
	v_lshl_add_u64 v[164:165], v[166:167], 0, s[38:39]
	s_addc_u32 s35, s35, 0
	s_add_i32 s36, s58, s46
	global_load_lds_dwordx4 v[164:165], off
	v_lshl_add_u64 v[164:165], s[34:35], 0, v[134:135]
	s_mov_b32 m0, s36
	s_nop 0
	global_load_lds_dwordx4 v[164:165], off
	v_lshl_add_u64 v[164:165], s[34:35], 0, v[130:131]
	s_add_i32 m0, s36, 0x2000
	s_nop 0
	global_load_lds_dwordx4 v[164:165], off
	v_lshl_add_u64 v[164:165], v[200:201], 0, s[38:39]
	s_mov_b32 m0, s0
	s_nop 0
	global_load_lds_dwordx4 v[164:165], off
	v_lshl_add_u64 v[164:165], v[248:249], 0, s[38:39]
	s_mov_b32 m0, s51
	s_nop 0
	global_load_lds_dwordx4 v[164:165], off
	s_waitcnt vmcnt(8)
	s_waitcnt lgkmcnt(0)
	s_barrier
	s_setprio 1
	s_waitcnt lgkmcnt(0)
	v_mfma_f32_16x16x32_bf16 v[62:65], v[142:145], v[196:199], v[62:65]
	v_mfma_f32_16x16x32_bf16 v[58:61], v[154:157], v[196:199], v[58:61]
	v_mfma_f32_16x16x32_bf16 v[46:49], v[142:145], v[224:227], v[46:49]
	v_mfma_f32_16x16x32_bf16 v[42:45], v[154:157], v[224:227], v[42:45]
	v_mfma_f32_16x16x32_bf16 v[28:31], v[142:145], v[232:235], v[28:31]
	v_mfma_f32_16x16x32_bf16 v[24:27], v[154:157], v[232:235], v[24:27]
	v_mfma_f32_16x16x32_bf16 v[12:15], v[142:145], v[240:243], v[12:15]
	v_mfma_f32_16x16x32_bf16 v[8:11], v[154:157], v[240:243], v[8:11]
	v_mfma_f32_16x16x32_bf16 v[62:65], v[146:149], v[220:223], v[62:65]
	v_mfma_f32_16x16x32_bf16 v[58:61], v[158:161], v[220:223], v[58:61]
	v_mfma_f32_16x16x32_bf16 v[46:49], v[146:149], v[228:231], v[46:49]
	v_mfma_f32_16x16x32_bf16 v[42:45], v[158:161], v[228:231], v[42:45]
	v_mfma_f32_16x16x32_bf16 v[28:31], v[146:149], v[236:239], v[28:31]
	v_mfma_f32_16x16x32_bf16 v[24:27], v[158:161], v[236:239], v[24:27]
	v_mfma_f32_16x16x32_bf16 v[12:15], v[146:149], v[244:247], v[12:15]
	v_mfma_f32_16x16x32_bf16 v[8:11], v[158:161], v[244:247], v[8:11]
	s_setprio 0
	s_setprio 1
	v_mfma_f32_16x16x32_bf16 v[54:57], v[180:183], v[196:199], v[54:57]
	v_mfma_f32_16x16x32_bf16 v[50:53], v[188:191], v[196:199], v[50:53]
	v_mfma_f32_16x16x32_bf16 v[38:41], v[180:183], v[224:227], v[38:41]
	v_mfma_f32_16x16x32_bf16 v[34:37], v[188:191], v[224:227], v[34:37]
	v_mfma_f32_16x16x32_bf16 v[20:23], v[180:183], v[232:235], v[20:23]
	v_mfma_f32_16x16x32_bf16 v[16:19], v[188:191], v[232:235], v[16:19]
	v_mfma_f32_16x16x32_bf16 v[4:7], v[180:183], v[240:243], v[4:7]
	v_mfma_f32_16x16x32_bf16 v[0:3], v[188:191], v[240:243], v[0:3]
	v_mfma_f32_16x16x32_bf16 v[54:57], v[184:187], v[220:223], v[54:57]
	v_mfma_f32_16x16x32_bf16 v[50:53], v[192:195], v[220:223], v[50:53]
	v_mfma_f32_16x16x32_bf16 v[38:41], v[184:187], v[228:231], v[38:41]
	v_mfma_f32_16x16x32_bf16 v[34:37], v[192:195], v[228:231], v[34:37]
	v_mfma_f32_16x16x32_bf16 v[20:23], v[184:187], v[236:239], v[20:23]
	v_mfma_f32_16x16x32_bf16 v[16:19], v[192:195], v[236:239], v[16:19]
	v_mfma_f32_16x16x32_bf16 v[4:7], v[184:187], v[244:247], v[4:7]
	v_mfma_f32_16x16x32_bf16 v[0:3], v[192:195], v[244:247], v[0:3]
	s_setprio 0
	s_barrier
	s_add_i32 s56, s56, 2
	s_add_u32 s30, s30, 0x100
	s_addc_u32 s31, s31, 0
	s_add_u32 s54, s54, 0x100
	s_addc_u32 s55, s55, 0
	s_cmp_gt_u32 s56, 29
	s_cbranch_scc0 .LBB0_735
	v_lshl_add_u32 v148, s22, 8, v33
	v_ashrrev_i32_e32 v149, 31, v148
	v_lshl_add_u64 v[144:145], v[148:149], 3, s[12:13]
	global_load_dwordx2 v[220:221], v[144:145], off
	global_load_dwordx2 v[222:223], v[144:145], off offset:128
	global_load_dwordx2 v[224:225], v[144:145], off offset:256
	global_load_dwordx2 v[226:227], v[144:145], off offset:384
	global_load_dwordx2 v[228:229], v[144:145], off offset:1024
	global_load_dwordx2 v[230:231], v[144:145], off offset:1152
	global_load_dwordx2 v[232:233], v[144:145], off offset:1280
	global_load_dwordx2 v[234:235], v[144:145], off offset:1408
	s_and_b64 vcc, exec, s[14:15]
	s_cbranch_vccz .LBB0_738
	s_barrier

; #define PG8_STAGE(bufoff, gbase, voff) do { _Pragma("unroll") for (int _i = 0; _i < 2; ++_i) \
;         __builtin_amdgcn_global_load_lds((const unsigned*)((const char*)(gbase) + (voff)[_i]), (PG8_LAS unsigned*)(lds + (bufoff) + ldsw + _i * 8192), 16, 0, 0); } while (0)
; #define PG8_WAIT_V(n) asm volatile("s_waitcnt vmcnt(" #n ")" ::: "memory")
; #define PG8_WAIT_L(n) asm volatile("s_waitcnt lgkmcnt(" #n ")" ::: "memory")
; #define PG8_BAR __builtin_amdgcn_s_barrier()
; #define PG8_SCHED __builtin_amdgcn_sched_barrier(0)
; template <class Epi, class Sched, bool ALIGN_EPI = false, bool SP2 = false, bool FP8 = false>
; __device__ __forceinline__ void gemm_phase(PG8_LAS unsigned char* lds, const Gemm g, const Sched& S, const Epi& E, const int tid) {
;     ...
;             PG8_WAIT_V(8); PG8_WAIT_L(0); PG8_BAR; PG8_MMA(1, 0, At, B0); PG8_MMA(1, 1, At, B1); PG8_BAR; PG8_SCHED;
;             PG8_LDB(B0, 1, 0); PG8_LDB(B1, 1, 1); PG8_SCHED; PG8_LDA(At, 1, 0); PG8_STAGE(PG8_SA(0, 1), a2 + hstepA, voffA);
;             PG8_WAIT_V(8); PG8_WAIT_L(0); PG8_BAR; PG8_MMA(0, 0, At, B0); PG8_MMA(0, 1, At, B1); PG8_BAR; PG8_SCHED;
.Lskw_5_1:
	s_waitcnt lgkmcnt(0)
	s_barrier
	s_setprio 1
	s_waitcnt lgkmcnt(0)
	s_nop 0
	v_mfma_f32_16x16x32_bf16 v[62:65], v[130:133], v[194:197], v[62:65]
	v_mfma_f32_16x16x32_bf16 v[58:61], v[138:141], v[194:197], v[58:61]
	v_mfma_f32_16x16x32_bf16 v[46:49], v[130:133], v[220:223], v[46:49]
	v_mfma_f32_16x16x32_bf16 v[42:45], v[138:141], v[220:223], v[42:45]
	v_mfma_f32_16x16x32_bf16 v[28:31], v[130:133], v[228:231], v[28:31]
	v_mfma_f32_16x16x32_bf16 v[24:27], v[138:141], v[228:231], v[24:27]
	v_mfma_f32_16x16x32_bf16 v[12:15], v[130:133], v[236:239], v[12:15]
	v_mfma_f32_16x16x32_bf16 v[8:11], v[138:141], v[236:239], v[8:11]
	v_mfma_f32_16x16x32_bf16 v[62:65], v[134:137], v[198:201], v[62:65]
	v_mfma_f32_16x16x32_bf16 v[58:61], v[154:157], v[198:201], v[58:61]
	v_mfma_f32_16x16x32_bf16 v[46:49], v[134:137], v[224:227], v[46:49]
	v_mfma_f32_16x16x32_bf16 v[42:45], v[154:157], v[224:227], v[42:45]
	v_mfma_f32_16x16x32_bf16 v[28:31], v[134:137], v[232:235], v[28:31]
	v_mfma_f32_16x16x32_bf16 v[24:27], v[154:157], v[232:235], v[24:27]
	v_mfma_f32_16x16x32_bf16 v[12:15], v[134:137], v[240:243], v[12:15]
	v_mfma_f32_16x16x32_bf16 v[8:11], v[154:157], v[240:243], v[8:11]
	s_setprio 0
	s_setprio 1
	v_mfma_f32_16x16x32_bf16 v[54:57], v[158:161], v[194:197], v[54:57]
	v_mfma_f32_16x16x32_bf16 v[50:53], v[184:187], v[194:197], v[50:53]
	v_mfma_f32_16x16x32_bf16 v[38:41], v[158:161], v[220:223], v[38:41]
	v_mfma_f32_16x16x32_bf16 v[34:37], v[184:187], v[220:223], v[34:37]
	v_mfma_f32_16x16x32_bf16 v[20:23], v[158:161], v[228:231], v[20:23]
	v_mfma_f32_16x16x32_bf16 v[16:19], v[184:187], v[228:231], v[16:19]
	v_mfma_f32_16x16x32_bf16 v[4:7], v[158:161], v[236:239], v[4:7]
	v_mfma_f32_16x16x32_bf16 v[0:3], v[184:187], v[236:239], v[0:3]
	v_mfma_f32_16x16x32_bf16 v[54:57], v[180:183], v[198:201], v[54:57]
	v_mfma_f32_16x16x32_bf16 v[50:53], v[190:193], v[198:201], v[50:53]
	v_mfma_f32_16x16x32_bf16 v[38:41], v[180:183], v[224:227], v[38:41]
	v_mfma_f32_16x16x32_bf16 v[34:37], v[190:193], v[224:227], v[34:37]
	v_mfma_f32_16x16x32_bf16 v[20:23], v[180:183], v[232:235], v[20:23]
	v_mfma_f32_16x16x32_bf16 v[16:19], v[190:193], v[232:235], v[16:19]
	v_mfma_f32_16x16x32_bf16 v[4:7], v[180:183], v[240:243], v[4:7]
	v_mfma_f32_16x16x32_bf16 v[0:3], v[190:193], v[240:243], v[0:3]
	s_setprio 0
	s_barrier
	s_add_i32 s63, 0, 0x18000
	s_add_i32 s64, 0, 0x1c000
	v_add_u32_e32 v154, s63, v163
	v_add_u32_e32 v189, s64, v163
	ds_read_b128 v[130:133], v154
	ds_read_b128 v[134:137], v154 offset:1024
	ds_read_b128 v[138:141], v154 offset:2048
	ds_read_b128 v[154:157], v154 offset:3072
	ds_read_b128 v[158:161], v189
	ds_read_b128 v[180:183], v189 offset:1024
	ds_read_b128 v[184:187], v189 offset:2048
	ds_read_b128 v[190:193], v189 offset:3072
	s_add_u32 s46, s46, 0x200000
	s_addc_u32 s47, s47, 0
	s_mov_b32 m0, s54
	v_lshl_add_u64 v[248:249], s[46:47], 0, v[148:149]
	ds_read_b128 v[194:197], v188 offset:32768
	ds_read_b128 v[198:201], v188 offset:33792
	ds_read_b128 v[220:223], v188 offset:34816
	ds_read_b128 v[224:227], v188 offset:35840
	ds_read_b128 v[228:231], v188 offset:36864
	ds_read_b128 v[232:235], v188 offset:37888
	ds_read_b128 v[236:239], v188 offset:38912
	ds_read_b128 v[240:243], v188 offset:39936
	global_load_lds_dwordx4 v[248:249], off
	v_lshl_add_u64 v[248:249], s[46:47], 0, v[144:145]
	s_mov_b32 m0, s55
	s_nop 0
	global_load_lds_dwordx4 v[248:249], off
	s_waitcnt vmcnt(8)
	s_waitcnt lgkmcnt(0)
	s_barrier
	s_setprio 1
	s_waitcnt lgkmcnt(0)
	s_nop 0
	v_mfma_f32_16x16x32_bf16 v[126:129], v[130:133], v[194:197], v[126:129]
	v_mfma_f32_16x16x32_bf16 v[122:125], v[138:141], v[194:197], v[122:125]
	v_mfma_f32_16x16x32_bf16 v[110:113], v[130:133], v[220:223], v[110:113]
	v_mfma_f32_16x16x32_bf16 v[106:109], v[138:141], v[220:223], v[106:109]
	v_mfma_f32_16x16x32_bf16 v[94:97], v[130:133], v[228:231], v[94:97]
	v_mfma_f32_16x16x32_bf16 v[90:93], v[138:141], v[228:231], v[90:93]
	v_mfma_f32_16x16x32_bf16 v[78:81], v[130:133], v[236:239], v[78:81]
	v_mfma_f32_16x16x32_bf16 v[74:77], v[138:141], v[236:239], v[74:77]
	v_mfma_f32_16x16x32_bf16 v[126:129], v[134:137], v[198:201], v[126:129]
	v_mfma_f32_16x16x32_bf16 v[122:125], v[154:157], v[198:201], v[122:125]
	v_mfma_f32_16x16x32_bf16 v[110:113], v[134:137], v[224:227], v[110:113]
	v_mfma_f32_16x16x32_bf16 v[106:109], v[154:157], v[224:227], v[106:109]
	v_mfma_f32_16x16x32_bf16 v[94:97], v[134:137], v[232:235], v[94:97]
	v_mfma_f32_16x16x32_bf16 v[90:93], v[154:157], v[232:235], v[90:93]
	v_mfma_f32_16x16x32_bf16 v[78:81], v[134:137], v[240:243], v[78:81]
	v_mfma_f32_16x16x32_bf16 v[74:77], v[154:157], v[240:243], v[74:77]
	s_setprio 0
	s_setprio 1
	v_mfma_f32_16x16x32_bf16 v[118:121], v[158:161], v[194:197], v[118:121]
	v_mfma_f32_16x16x32_bf16 v[114:117], v[184:187], v[194:197], v[114:117]
	v_mfma_f32_16x16x32_bf16 v[102:105], v[158:161], v[220:223], v[102:105]
	v_mfma_f32_16x16x32_bf16 v[98:101], v[184:187], v[220:223], v[98:101]
	v_mfma_f32_16x16x32_bf16 v[86:89], v[158:161], v[228:231], v[86:89]
	v_mfma_f32_16x16x32_bf16 v[82:85], v[184:187], v[228:231], v[82:85]
	v_mfma_f32_16x16x32_bf16 v[70:73], v[158:161], v[236:239], v[70:73]
	v_mfma_f32_16x16x32_bf16 v[66:69], v[184:187], v[236:239], v[66:69]
	v_mfma_f32_16x16x32_bf16 v[118:121], v[180:183], v[198:201], v[118:121]
	v_mfma_f32_16x16x32_bf16 v[114:117], v[190:193], v[198:201], v[114:117]
	v_mfma_f32_16x16x32_bf16 v[102:105], v[180:183], v[224:227], v[102:105]
	v_mfma_f32_16x16x32_bf16 v[98:101], v[190:193], v[224:227], v[98:101]
	v_mfma_f32_16x16x32_bf16 v[86:89], v[180:183], v[232:235], v[86:89]
	v_mfma_f32_16x16x32_bf16 v[82:85], v[190:193], v[232:235], v[82:85]
	v_mfma_f32_16x16x32_bf16 v[70:73], v[180:183], v[240:243], v[70:73]
	v_mfma_f32_16x16x32_bf16 v[66:69], v[190:193], v[240:243], v[66:69]
	s_setprio 0
	s_barrier
; #define PG8_STAGE(bufoff, gbase, voff) do { _Pragma("unroll") for (int _i = 0; _i < 2; ++_i) \
;         __builtin_amdgcn_global_load_lds((const unsigned*)((const char*)(gbase) + (voff)[_i]), (PG8_LAS unsigned*)(lds + (bufoff) + ldsw + _i * 8192), 16, 0, 0); } while (0)
; #define PG8_WAIT_V(n) asm volatile("s_waitcnt vmcnt(" #n ")" ::: "memory")
; #define PG8_WAIT_L(n) asm volatile("s_waitcnt lgkmcnt(" #n ")" ::: "memory")
; #define PG8_BAR __builtin_amdgcn_s_barrier()
; #define PG8_SCHED __builtin_amdgcn_sched_barrier(0)
; template <class Epi, class Sched, bool ALIGN_EPI = false, bool SP2 = false, bool FP8 = false>
; __device__ __forceinline__ void gemm_phase(PG8_LAS unsigned char* lds, const Gemm g, const Sched& S, const Epi& E, const int tid) {
;     ...
;             PG8_LDA(At, 1, 1); PG8_STAGE(PG8_SB(1, 0), b3, voffB); PG8_STAGE(PG8_SB(1, 1), b3 + hstepB, voffB); PG8_STAGE(PG8_SA(1, 0), a3, voffA);
;             PG8_WAIT_V(8); PG8_WAIT_L(0); PG8_BAR; PG8_MMA(1, 0, At, B0); PG8_MMA(1, 1, At, B1); PG8_BAR; PG8_SCHED;
	s_add_i32 s46, s63, s51
	v_lshl_add_u64 v[164:165], v[164:165], 0, s[38:39]
	s_mov_b32 m0, s46
	ds_read_b128 v[194:197], v188 offset:49152
	ds_read_b128 v[198:201], v188 offset:50176
	ds_read_b128 v[220:223], v188 offset:51200
	ds_read_b128 v[224:227], v188 offset:52224
	ds_read_b128 v[228:231], v188 offset:53248
	ds_read_b128 v[232:235], v188 offset:54272
	ds_read_b128 v[236:239], v188 offset:55296
	ds_read_b128 v[240:243], v188 offset:56320
	global_load_lds_dwordx4 v[164:165], off
	s_add_i32 m0, s46, 0x2000
	s_add_u32 s10, s10, 0x200080
	v_lshl_add_u64 v[164:165], v[166:167], 0, s[38:39]
	s_addc_u32 s11, s11, 0
	s_add_i32 s46, s64, s51
	global_load_lds_dwordx4 v[164:165], off
	v_lshl_add_u64 v[164:165], s[10:11], 0, v[146:147]
	s_mov_b32 m0, s46
	s_nop 0
	global_load_lds_dwordx4 v[164:165], off
	v_lshl_add_u64 v[164:165], s[10:11], 0, v[142:143]
	s_add_i32 m0, s46, 0x2000
	s_nop 0
	global_load_lds_dwordx4 v[164:165], off
	v_lshl_add_u64 v[164:165], v[244:245], 0, s[38:39]
	s_mov_b32 m0, s56
	s_nop 0
	global_load_lds_dwordx4 v[164:165], off
	v_lshl_add_u64 v[164:165], v[246:247], 0, s[38:39]
	s_mov_b32 m0, s57
	s_nop 0
	global_load_lds_dwordx4 v[164:165], off
	s_waitcnt vmcnt(8)
	s_waitcnt lgkmcnt(0)
	s_barrier
	s_setprio 1
	s_waitcnt lgkmcnt(0)
	v_mfma_f32_16x16x32_bf16 v[62:65], v[130:133], v[194:197], v[62:65]
	v_mfma_f32_16x16x32_bf16 v[58:61], v[138:141], v[194:197], v[58:61]
	v_mfma_f32_16x16x32_bf16 v[46:49], v[130:133], v[220:223], v[46:49]
	v_mfma_f32_16x16x32_bf16 v[42:45], v[138:141], v[220:223], v[42:45]
	v_mfma_f32_16x16x32_bf16 v[28:31], v[130:133], v[228:231], v[28:31]
	v_mfma_f32_16x16x32_bf16 v[24:27], v[138:141], v[228:231], v[24:27]
	v_mfma_f32_16x16x32_bf16 v[12:15], v[130:133], v[236:239], v[12:15]
	v_mfma_f32_16x16x32_bf16 v[8:11], v[138:141], v[236:239], v[8:11]
	v_mfma_f32_16x16x32_bf16 v[62:65], v[134:137], v[198:201], v[62:65]
	v_mfma_f32_16x16x32_bf16 v[58:61], v[154:157], v[198:201], v[58:61]
	v_mfma_f32_16x16x32_bf16 v[46:49], v[134:137], v[224:227], v[46:49]
	v_mfma_f32_16x16x32_bf16 v[42:45], v[154:157], v[224:227], v[42:45]
	v_mfma_f32_16x16x32_bf16 v[28:31], v[134:137], v[232:235], v[28:31]
	v_mfma_f32_16x16x32_bf16 v[24:27], v[154:157], v[232:235], v[24:27]
	v_mfma_f32_16x16x32_bf16 v[12:15], v[134:137], v[240:243], v[12:15]
	v_mfma_f32_16x16x32_bf16 v[8:11], v[154:157], v[240:243], v[8:11]
	s_setprio 0
	s_setprio 1
	v_mfma_f32_16x16x32_bf16 v[54:57], v[158:161], v[194:197], v[54:57]
	v_mfma_f32_16x16x32_bf16 v[50:53], v[184:187], v[194:197], v[50:53]
	v_mfma_f32_16x16x32_bf16 v[38:41], v[158:161], v[220:223], v[38:41]
	v_mfma_f32_16x16x32_bf16 v[34:37], v[184:187], v[220:223], v[34:37]
	v_mfma_f32_16x16x32_bf16 v[20:23], v[158:161], v[228:231], v[20:23]
	v_mfma_f32_16x16x32_bf16 v[16:19], v[184:187], v[228:231], v[16:19]
	v_mfma_f32_16x16x32_bf16 v[4:7], v[158:161], v[236:239], v[4:7]
	v_mfma_f32_16x16x32_bf16 v[0:3], v[184:187], v[236:239], v[0:3]
	v_mfma_f32_16x16x32_bf16 v[54:57], v[180:183], v[198:201], v[54:57]
	v_mfma_f32_16x16x32_bf16 v[50:53], v[190:193], v[198:201], v[50:53]
	v_mfma_f32_16x16x32_bf16 v[38:41], v[180:183], v[224:227], v[38:41]
	v_mfma_f32_16x16x32_bf16 v[34:37], v[190:193], v[224:227], v[34:37]
	v_mfma_f32_16x16x32_bf16 v[20:23], v[180:183], v[232:235], v[20:23]
	v_mfma_f32_16x16x32_bf16 v[16:19], v[190:193], v[232:235], v[16:19]
	v_mfma_f32_16x16x32_bf16 v[4:7], v[180:183], v[240:243], v[4:7]
	v_mfma_f32_16x16x32_bf16 v[0:3], v[190:193], v[240:243], v[0:3]
	s_setprio 0
	s_barrier
	s_add_i32 s62, s62, 2
	s_add_u32 s8, s8, 0x100
	s_addc_u32 s9, s9, 0
	s_add_u32 s60, s60, 0x100
	s_addc_u32 s61, s61, 0
	s_cmpk_gt_u32 s62, 0x7d
	s_cbranch_scc0 .LBB0_801
	s_and_b64 vcc, exec, s[30:31]
	s_cbranch_vccz .LBB0_804
	s_barrier
